# GEMM K-loops with inverted priority: the LDS-read / LDS-DMA segment runs at s_setprio 1, the MFMA segment at 0
# baseline (speedup 1.0000x reference)
; #define PG8_STAGE(bufoff, gbase, voff) do { _Pragma("unroll") for (int _i = 0; _i < 2; ++_i) \
;         __builtin_amdgcn_global_load_lds((const unsigned*)((const char*)(gbase) + (voff)[_i]), (PG8_LAS unsigned*)(lds + (bufoff) + ldsw + _i * 8192), 16, 0, 0); } while (0)
; #define PG8_LDA(dst, b, h) do { _Pragma("unroll") for (int m = 0; m < 4; ++m) _Pragma("unroll") for (int k = 0; k < 2; ++k) dst[m][k] = *(const PG8_LAS bf16x8*)(lds + PG8_SA(b, h) + aoff + m * 2048 + k * 1024); } while (0)
; #define PG8_LDB(dst, b, h) do { _Pragma("unroll") for (int n = 0; n < 2; ++n) _Pragma("unroll") for (int k = 0; k < 2; ++k) dst[n][k] = *(const PG8_LAS bf16x8*)(lds + PG8_SB(b, h) + boff + n * 2048 + k * 1024); } while (0)
; #define PG8_MMA(ai, bj, At, Bt) do { __builtin_amdgcn_s_setprio(1); _Pragma("unroll") for (int m = 0; m < 4; ++m) _Pragma("unroll") for (int n = 0; n < 2; ++n) _Pragma("unroll") for (int k = 0; k < 2; ++k) \
;         acc[ai][bj][m][n] = __builtin_amdgcn_mfma_f32_16x16x32_bf16(Bt[n][k], At[m][k], acc[ai][bj][m][n], 0, 0, 0); __builtin_amdgcn_s_setprio(0); } while (0)
; #define PG8_WAIT_V(n) asm volatile("s_waitcnt vmcnt(" #n ")" ::: "memory")
; #define PG8_WAIT_L(n) asm volatile("s_waitcnt lgkmcnt(" #n ")" ::: "memory")
; template <class Epi, class Sched, bool ALIGN_EPI = false, bool SP2 = false>
; __device__ __forceinline__ void gemm_phase(PG8_LAS unsigned char* lds, const Gemm g, const Sched& S, const Epi& E) {
;     ...
;             const bool last = (t == nt - 2);
;             const char* a1 = cA + (size_t)(t + 1) * kstep;
;             const char* a2 = last ? nA : cA + (size_t)(t + 2) * kstep; const char* b2 = last ? nB : cB + (size_t)(t + 2) * kstep;
;             const char* a3 = a2 + kstep; const char* b3 = b2 + kstep;
;             if (last && has_next) S.a_ready(nxt);
;             if constexpr (SP2) {
;             PG8_LDB(B0, 0, 0); PG8_LDB(B1, 0, 1); PG8_SCHED; PG8_LDA(At, 0, 0); PG8_STAGE(PG8_SA(1, 1), a1 + hstep, voffA);
;             PG8_WAIT_V(8); PG8_WAIT_L(0); PG8_BAR; PG8_MMA(0, 0, At, B0); PG8_MMA(0, 1, At, B1); PG8_BAR; PG8_SCHED;
;             PG8_LDA(At, 0, 1); PG8_STAGE(PG8_SB(0, 0), b2, voffB); PG8_STAGE(PG8_SB(0, 1), b2 + hstepB, voffB); PG8_STAGE(PG8_SA(0, 0), a2, voffA);
;             PG8_WAIT_V(8); PG8_WAIT_L(0); PG8_BAR; PG8_MMA(1, 0, At, B0); PG8_MMA(1, 1, At, B1); PG8_BAR; PG8_SCHED;
.LBB0_170:
	s_add_u32 s9, s70, s46
	s_addc_u32 s10, s71, s47
	s_add_u32 s9, s9, 0x100
	s_addc_u32 s10, s10, 0
	s_add_u32 s11, s93, s46
	s_addc_u32 s12, s94, s47
	s_add_i32 s13, 0, 0x10000
	s_cmpk_eq_i32 s46, 0xf00
	s_cselect_b32 s85, s4, s10
	s_cselect_b32 s84, s5, s9
	s_cselect_b32 s81, s6, s12
	s_cselect_b32 s80, s7, s11
	s_add_i32 s9, 0, 0x14000
	v_add_u32_e32 v160, s13, v139
	v_add_u32_e32 v178, s9, v139
	ds_read_b128 v[148:151], v160
	ds_read_b128 v[152:155], v160 offset:1024
	ds_read_b128 v[156:159], v160 offset:2048
	ds_read_b128 v[160:163], v160 offset:3072
	ds_read_b128 v[166:169], v178
	ds_read_b128 v[170:173], v178 offset:1024
	ds_read_b128 v[174:177], v178 offset:2048
	ds_read_b128 v[178:181], v178 offset:3072
	v_lshl_add_u64 v[194:195], v[144:145], 0, s[46:47]
	s_add_i32 m0, s1, 0xc000
	ds_read_b128 v[182:185], v165
	ds_read_b128 v[206:209], v165 offset:1024
	ds_read_b128 v[210:213], v165 offset:2048
	ds_read_b128 v[214:217], v165 offset:3072
	ds_read_b128 v[218:221], v165 offset:4096
	ds_read_b128 v[236:239], v165 offset:5120
	ds_read_b128 v[240:243], v165 offset:6144
	ds_read_b128 v[244:247], v165 offset:7168
	global_load_lds_dwordx4 v[194:195], off
	v_lshl_add_u64 v[194:195], v[146:147], 0, s[46:47]
	s_add_i32 m0, s1, 0xe000
	s_nop 0
	global_load_lds_dwordx4 v[194:195], off
	s_waitcnt vmcnt(8)
	s_waitcnt lgkmcnt(0)
	s_barrier
	s_setprio 0
	s_waitcnt lgkmcnt(0)
	v_mfma_f32_16x16x32_bf16 v[126:129], v[148:151], v[182:185], v[126:129]
	v_mfma_f32_16x16x32_bf16 v[122:125], v[156:159], v[182:185], v[122:125]
	v_mfma_f32_16x16x32_bf16 v[118:121], v[148:151], v[210:213], v[118:121]
	v_mfma_f32_16x16x32_bf16 v[114:117], v[156:159], v[210:213], v[114:117]
	v_mfma_f32_16x16x32_bf16 v[110:113], v[148:151], v[218:221], v[110:113]
	v_mfma_f32_16x16x32_bf16 v[106:109], v[156:159], v[218:221], v[106:109]
	v_mfma_f32_16x16x32_bf16 v[102:105], v[148:151], v[240:243], v[102:105]
	v_mfma_f32_16x16x32_bf16 v[98:101], v[156:159], v[240:243], v[98:101]
	v_mfma_f32_16x16x32_bf16 v[126:129], v[152:155], v[206:209], v[126:129]
	v_mfma_f32_16x16x32_bf16 v[122:125], v[160:163], v[206:209], v[122:125]
	v_mfma_f32_16x16x32_bf16 v[118:121], v[152:155], v[214:217], v[118:121]
	v_mfma_f32_16x16x32_bf16 v[114:117], v[160:163], v[214:217], v[114:117]
	v_mfma_f32_16x16x32_bf16 v[110:113], v[152:155], v[236:239], v[110:113]
	v_mfma_f32_16x16x32_bf16 v[106:109], v[160:163], v[236:239], v[106:109]
	v_mfma_f32_16x16x32_bf16 v[102:105], v[152:155], v[244:247], v[102:105]
	v_mfma_f32_16x16x32_bf16 v[98:101], v[160:163], v[244:247], v[98:101]
	v_mfma_f32_16x16x32_bf16 v[94:97], v[166:169], v[182:185], v[94:97]
	v_mfma_f32_16x16x32_bf16 v[90:93], v[174:177], v[182:185], v[90:93]
	v_mfma_f32_16x16x32_bf16 v[86:89], v[166:169], v[210:213], v[86:89]
	v_mfma_f32_16x16x32_bf16 v[82:85], v[174:177], v[210:213], v[82:85]
	v_mfma_f32_16x16x32_bf16 v[78:81], v[166:169], v[218:221], v[78:81]
	v_mfma_f32_16x16x32_bf16 v[74:77], v[174:177], v[218:221], v[74:77]
	v_mfma_f32_16x16x32_bf16 v[70:73], v[166:169], v[240:243], v[70:73]
	v_mfma_f32_16x16x32_bf16 v[66:69], v[174:177], v[240:243], v[66:69]
	v_mfma_f32_16x16x32_bf16 v[94:97], v[170:173], v[206:209], v[94:97]
	v_mfma_f32_16x16x32_bf16 v[90:93], v[178:181], v[206:209], v[90:93]
	v_mfma_f32_16x16x32_bf16 v[86:89], v[170:173], v[214:217], v[86:89]
	v_mfma_f32_16x16x32_bf16 v[82:85], v[178:181], v[214:217], v[82:85]
	v_mfma_f32_16x16x32_bf16 v[78:81], v[170:173], v[236:239], v[78:81]
	v_mfma_f32_16x16x32_bf16 v[74:77], v[178:181], v[236:239], v[74:77]
	v_mfma_f32_16x16x32_bf16 v[70:73], v[170:173], v[244:247], v[70:73]
	v_mfma_f32_16x16x32_bf16 v[66:69], v[178:181], v[244:247], v[66:69]
	s_setprio 1
	s_barrier
	s_add_i32 s10, s13, s0
	v_lshl_add_u64 v[194:195], s[80:81], 0, v[132:133]
	s_mov_b32 m0, s10
	ds_read_b128 v[182:185], v165 offset:16384
	ds_read_b128 v[206:209], v165 offset:17408
	ds_read_b128 v[210:213], v165 offset:18432
	ds_read_b128 v[214:217], v165 offset:19456
	ds_read_b128 v[218:221], v165 offset:20480
	ds_read_b128 v[236:239], v165 offset:21504
	ds_read_b128 v[240:243], v165 offset:22528
	ds_read_b128 v[244:247], v165 offset:23552
	global_load_lds_dwordx4 v[194:195], off
	s_add_i32 m0, s10, 0x2000
	s_add_u32 s10, s80, 0x20000
	v_lshl_add_u64 v[196:197], s[80:81], 0, v[136:137]
	s_addc_u32 s11, s81, 0
	s_add_i32 s9, s9, s0
	global_load_lds_dwordx4 v[196:197], off
	v_lshl_add_u64 v[222:223], s[10:11], 0, v[132:133]
	s_mov_b32 m0, s9
	v_lshl_add_u64 v[234:235], s[84:85], 0, v[134:135]
	global_load_lds_dwordx4 v[222:223], off
	v_lshl_add_u64 v[222:223], s[10:11], 0, v[136:137]
	s_add_i32 m0, s9, 0x2000
	s_nop 0
	global_load_lds_dwordx4 v[222:223], off
	v_lshl_add_u64 v[222:223], s[84:85], 0, v[130:131]
	s_mov_b32 m0, s1
	s_nop 0
	global_load_lds_dwordx4 v[222:223], off
	s_mov_b32 m0, s25
	s_nop 0
	global_load_lds_dwordx4 v[234:235], off
	s_waitcnt vmcnt(8)
	s_waitcnt lgkmcnt(0)
	s_barrier
; #define PG8_STAGE(bufoff, gbase, voff) do { _Pragma("unroll") for (int _i = 0; _i < 2; ++_i) \
;         __builtin_amdgcn_global_load_lds((const unsigned*)((const char*)(gbase) + (voff)[_i]), (PG8_LAS unsigned*)(lds + (bufoff) + ldsw + _i * 8192), 16, 0, 0); } while (0)
; #define PG8_LDA(dst, b, h) do { _Pragma("unroll") for (int m = 0; m < 4; ++m) _Pragma("unroll") for (int k = 0; k < 2; ++k) dst[m][k] = *(const PG8_LAS bf16x8*)(lds + PG8_SA(b, h) + aoff + m * 2048 + k * 1024); } while (0)
; #define PG8_LDB(dst, b, h) do { _Pragma("unroll") for (int n = 0; n < 2; ++n) _Pragma("unroll") for (int k = 0; k < 2; ++k) dst[n][k] = *(const PG8_LAS bf16x8*)(lds + PG8_SB(b, h) + boff + n * 2048 + k * 1024); } while (0)
; #define PG8_MMA(ai, bj, At, Bt) do { __builtin_amdgcn_s_setprio(1); _Pragma("unroll") for (int m = 0; m < 4; ++m) _Pragma("unroll") for (int n = 0; n < 2; ++n) _Pragma("unroll") for (int k = 0; k < 2; ++k) \
;         acc[ai][bj][m][n] = __builtin_amdgcn_mfma_f32_16x16x32_bf16(Bt[n][k], At[m][k], acc[ai][bj][m][n], 0, 0, 0); __builtin_amdgcn_s_setprio(0); } while (0)
; #define PG8_WAIT_V(n) asm volatile("s_waitcnt vmcnt(" #n ")" ::: "memory")
; #define PG8_WAIT_L(n) asm volatile("s_waitcnt lgkmcnt(" #n ")" ::: "memory")
; #define PG8_BAR __builtin_amdgcn_s_barrier()
; #define PG8_SCHED __builtin_amdgcn_sched_barrier(0)
; template <class Epi, class Sched, bool ALIGN_EPI = false, bool SP2 = false>
; __device__ __forceinline__ void gemm_phase(PG8_LAS unsigned char* lds, const Gemm g, const Sched& S, const Epi& E) {
;     ...
;             PG8_WAIT_V(8); PG8_WAIT_L(0); PG8_BAR; PG8_MMA(1, 0, At, B0); PG8_MMA(1, 1, At, B1); PG8_BAR; PG8_SCHED;
;             PG8_LDB(B0, 1, 0); PG8_LDB(B1, 1, 1); PG8_SCHED; PG8_LDA(At, 1, 0); PG8_STAGE(PG8_SA(0, 1), a2 + hstep, voffA);
;             PG8_WAIT_V(8); PG8_WAIT_L(0); PG8_BAR; PG8_MMA(0, 0, At, B0); PG8_MMA(0, 1, At, B1); PG8_BAR; PG8_SCHED;
	s_setprio 0
	s_waitcnt lgkmcnt(0)
	v_mfma_f32_16x16x32_bf16 v[62:65], v[148:151], v[182:185], v[62:65]
	v_mfma_f32_16x16x32_bf16 v[58:61], v[156:159], v[182:185], v[58:61]
	v_mfma_f32_16x16x32_bf16 v[54:57], v[148:151], v[210:213], v[54:57]
	v_mfma_f32_16x16x32_bf16 v[50:53], v[156:159], v[210:213], v[50:53]
	v_mfma_f32_16x16x32_bf16 v[46:49], v[148:151], v[218:221], v[46:49]
	v_mfma_f32_16x16x32_bf16 v[42:45], v[156:159], v[218:221], v[42:45]
	v_mfma_f32_16x16x32_bf16 v[38:41], v[148:151], v[240:243], v[38:41]
	v_mfma_f32_16x16x32_bf16 v[34:37], v[156:159], v[240:243], v[34:37]
	v_mfma_f32_16x16x32_bf16 v[62:65], v[152:155], v[206:209], v[62:65]
	v_mfma_f32_16x16x32_bf16 v[58:61], v[160:163], v[206:209], v[58:61]
	v_mfma_f32_16x16x32_bf16 v[54:57], v[152:155], v[214:217], v[54:57]
	v_mfma_f32_16x16x32_bf16 v[50:53], v[160:163], v[214:217], v[50:53]
	v_mfma_f32_16x16x32_bf16 v[46:49], v[152:155], v[236:239], v[46:49]
	v_mfma_f32_16x16x32_bf16 v[42:45], v[160:163], v[236:239], v[42:45]
	v_mfma_f32_16x16x32_bf16 v[38:41], v[152:155], v[244:247], v[38:41]
	v_mfma_f32_16x16x32_bf16 v[34:37], v[160:163], v[244:247], v[34:37]
	v_mfma_f32_16x16x32_bf16 v[30:33], v[166:169], v[182:185], v[30:33]
	v_mfma_f32_16x16x32_bf16 v[26:29], v[174:177], v[182:185], v[26:29]
	v_mfma_f32_16x16x32_bf16 v[22:25], v[166:169], v[210:213], v[22:25]
	v_mfma_f32_16x16x32_bf16 v[18:21], v[174:177], v[210:213], v[18:21]
	v_mfma_f32_16x16x32_bf16 v[14:17], v[166:169], v[218:221], v[14:17]
	v_mfma_f32_16x16x32_bf16 v[10:13], v[174:177], v[218:221], v[10:13]
	v_mfma_f32_16x16x32_bf16 v[6:9], v[166:169], v[240:243], v[6:9]
	v_mfma_f32_16x16x32_bf16 v[2:5], v[174:177], v[240:243], v[2:5]
	v_mfma_f32_16x16x32_bf16 v[30:33], v[170:173], v[206:209], v[30:33]
	v_mfma_f32_16x16x32_bf16 v[26:29], v[178:181], v[206:209], v[26:29]
	v_mfma_f32_16x16x32_bf16 v[22:25], v[170:173], v[214:217], v[22:25]
	v_mfma_f32_16x16x32_bf16 v[18:21], v[178:181], v[214:217], v[18:21]
	v_mfma_f32_16x16x32_bf16 v[14:17], v[170:173], v[236:239], v[14:17]
	v_mfma_f32_16x16x32_bf16 v[10:13], v[178:181], v[236:239], v[10:13]
	v_mfma_f32_16x16x32_bf16 v[6:9], v[170:173], v[244:247], v[6:9]
	v_mfma_f32_16x16x32_bf16 v[2:5], v[178:181], v[244:247], v[2:5]
	s_setprio 1
	s_barrier
	s_add_i32 s9, 0, 0x18000
	s_add_i32 s12, 0, 0x1c000
	v_add_u32_e32 v160, s9, v139
	v_add_u32_e32 v178, s12, v139
	ds_read_b128 v[148:151], v160
	ds_read_b128 v[152:155], v160 offset:1024
	ds_read_b128 v[156:159], v160 offset:2048
	ds_read_b128 v[160:163], v160 offset:3072
	ds_read_b128 v[166:169], v178
	ds_read_b128 v[170:173], v178 offset:1024
	ds_read_b128 v[174:177], v178 offset:2048
	ds_read_b128 v[178:181], v178 offset:3072
	s_add_u32 s10, s84, 0x80000
	s_addc_u32 s11, s85, 0
	s_mov_b32 m0, s42
	v_lshl_add_u64 v[198:199], s[10:11], 0, v[130:131]
	ds_read_b128 v[182:185], v165 offset:32768
	ds_read_b128 v[206:209], v165 offset:33792
	ds_read_b128 v[210:213], v165 offset:34816
	ds_read_b128 v[214:217], v165 offset:35840
	ds_read_b128 v[218:221], v165 offset:36864
	ds_read_b128 v[236:239], v165 offset:37888
	ds_read_b128 v[240:243], v165 offset:38912
	ds_read_b128 v[244:247], v165 offset:39936
	global_load_lds_dwordx4 v[198:199], off
	v_lshl_add_u64 v[198:199], s[10:11], 0, v[134:135]
	s_mov_b32 m0, s51
	s_nop 0
	global_load_lds_dwordx4 v[198:199], off
	s_waitcnt vmcnt(8)
	s_waitcnt lgkmcnt(0)
	s_barrier
	s_setprio 0
	s_waitcnt lgkmcnt(0)
	v_mfma_f32_16x16x32_bf16 v[126:129], v[148:151], v[182:185], v[126:129]
	v_mfma_f32_16x16x32_bf16 v[122:125], v[156:159], v[182:185], v[122:125]
	v_mfma_f32_16x16x32_bf16 v[118:121], v[148:151], v[210:213], v[118:121]
	v_mfma_f32_16x16x32_bf16 v[114:117], v[156:159], v[210:213], v[114:117]
	v_mfma_f32_16x16x32_bf16 v[110:113], v[148:151], v[218:221], v[110:113]
	v_mfma_f32_16x16x32_bf16 v[106:109], v[156:159], v[218:221], v[106:109]
	v_mfma_f32_16x16x32_bf16 v[102:105], v[148:151], v[240:243], v[102:105]
	v_mfma_f32_16x16x32_bf16 v[98:101], v[156:159], v[240:243], v[98:101]
	v_mfma_f32_16x16x32_bf16 v[126:129], v[152:155], v[206:209], v[126:129]
	v_mfma_f32_16x16x32_bf16 v[122:125], v[160:163], v[206:209], v[122:125]
	v_mfma_f32_16x16x32_bf16 v[118:121], v[152:155], v[214:217], v[118:121]
	v_mfma_f32_16x16x32_bf16 v[114:117], v[160:163], v[214:217], v[114:117]
	v_mfma_f32_16x16x32_bf16 v[110:113], v[152:155], v[236:239], v[110:113]
	v_mfma_f32_16x16x32_bf16 v[106:109], v[160:163], v[236:239], v[106:109]
	v_mfma_f32_16x16x32_bf16 v[102:105], v[152:155], v[244:247], v[102:105]
	v_mfma_f32_16x16x32_bf16 v[98:101], v[160:163], v[244:247], v[98:101]
	v_mfma_f32_16x16x32_bf16 v[94:97], v[166:169], v[182:185], v[94:97]
	v_mfma_f32_16x16x32_bf16 v[90:93], v[174:177], v[182:185], v[90:93]
	v_mfma_f32_16x16x32_bf16 v[86:89], v[166:169], v[210:213], v[86:89]
	v_mfma_f32_16x16x32_bf16 v[82:85], v[174:177], v[210:213], v[82:85]
	v_mfma_f32_16x16x32_bf16 v[78:81], v[166:169], v[218:221], v[78:81]
	v_mfma_f32_16x16x32_bf16 v[74:77], v[174:177], v[218:221], v[74:77]
	v_mfma_f32_16x16x32_bf16 v[70:73], v[166:169], v[240:243], v[70:73]
	v_mfma_f32_16x16x32_bf16 v[66:69], v[174:177], v[240:243], v[66:69]
	v_mfma_f32_16x16x32_bf16 v[94:97], v[170:173], v[206:209], v[94:97]
	v_mfma_f32_16x16x32_bf16 v[90:93], v[178:181], v[206:209], v[90:93]
	v_mfma_f32_16x16x32_bf16 v[86:89], v[170:173], v[214:217], v[86:89]
	v_mfma_f32_16x16x32_bf16 v[82:85], v[178:181], v[214:217], v[82:85]
	v_mfma_f32_16x16x32_bf16 v[78:81], v[170:173], v[236:239], v[78:81]
	v_mfma_f32_16x16x32_bf16 v[74:77], v[178:181], v[236:239], v[74:77]
	v_mfma_f32_16x16x32_bf16 v[70:73], v[170:173], v[244:247], v[70:73]
	v_mfma_f32_16x16x32_bf16 v[66:69], v[178:181], v[244:247], v[66:69]
	s_setprio 1
	s_barrier
; #define PG8_STAGE(bufoff, gbase, voff) do { _Pragma("unroll") for (int _i = 0; _i < 2; ++_i) \
;         __builtin_amdgcn_global_load_lds((const unsigned*)((const char*)(gbase) + (voff)[_i]), (PG8_LAS unsigned*)(lds + (bufoff) + ldsw + _i * 8192), 16, 0, 0); } while (0)
; #define PG8_LDA(dst, b, h) do { _Pragma("unroll") for (int m = 0; m < 4; ++m) _Pragma("unroll") for (int k = 0; k < 2; ++k) dst[m][k] = *(const PG8_LAS bf16x8*)(lds + PG8_SA(b, h) + aoff + m * 2048 + k * 1024); } while (0)
; #define PG8_MMA(ai, bj, At, Bt) do { __builtin_amdgcn_s_setprio(1); _Pragma("unroll") for (int m = 0; m < 4; ++m) _Pragma("unroll") for (int n = 0; n < 2; ++n) _Pragma("unroll") for (int k = 0; k < 2; ++k) \
;         acc[ai][bj][m][n] = __builtin_amdgcn_mfma_f32_16x16x32_bf16(Bt[n][k], At[m][k], acc[ai][bj][m][n], 0, 0, 0); __builtin_amdgcn_s_setprio(0); } while (0)
; #define PG8_WAIT_V(n) asm volatile("s_waitcnt vmcnt(" #n ")" ::: "memory")
; #define PG8_WAIT_L(n) asm volatile("s_waitcnt lgkmcnt(" #n ")" ::: "memory")
; #define PG8_BAR __builtin_amdgcn_s_barrier()
; #define PG8_SCHED __builtin_amdgcn_sched_barrier(0)
; template <class Epi, class Sched, bool ALIGN_EPI = false, bool SP2 = false>
; __device__ __forceinline__ void gemm_phase(PG8_LAS unsigned char* lds, const Gemm g, const Sched& S, const Epi& E) {
;     ...
;             PG8_LDA(At, 1, 1); PG8_STAGE(PG8_SB(1, 0), b3, voffB); PG8_STAGE(PG8_SB(1, 1), b3 + hstepB, voffB); PG8_STAGE(PG8_SA(1, 0), a3, voffA);
;             PG8_WAIT_V(8); PG8_WAIT_L(0); PG8_BAR; PG8_MMA(1, 0, At, B0); PG8_MMA(1, 1, At, B1); PG8_BAR; PG8_SCHED;
	s_add_i32 s9, s9, s0
	v_lshl_add_u64 v[194:195], v[194:195], 0, s[60:61]
	s_mov_b32 m0, s9
	ds_read_b128 v[182:185], v165 offset:49152
	ds_read_b128 v[206:209], v165 offset:50176
	ds_read_b128 v[210:213], v165 offset:51200
	ds_read_b128 v[214:217], v165 offset:52224
	ds_read_b128 v[218:221], v165 offset:53248
	ds_read_b128 v[236:239], v165 offset:54272
	ds_read_b128 v[240:243], v165 offset:55296
	ds_read_b128 v[244:247], v165 offset:56320
	global_load_lds_dwordx4 v[194:195], off
	s_add_i32 m0, s9, 0x2000
	s_add_u32 s10, s80, 0x20080
	v_lshl_add_u64 v[194:195], v[196:197], 0, s[60:61]
	s_addc_u32 s11, s81, 0
	s_add_i32 s9, s12, s0
	global_load_lds_dwordx4 v[194:195], off
	v_lshl_add_u64 v[194:195], s[10:11], 0, v[132:133]
	s_mov_b32 m0, s9
	s_nop 0
	global_load_lds_dwordx4 v[194:195], off
	v_lshl_add_u64 v[194:195], s[10:11], 0, v[136:137]
	s_add_i32 m0, s9, 0x2000
	s_nop 0
	global_load_lds_dwordx4 v[194:195], off
	v_lshl_add_u64 v[194:195], v[222:223], 0, s[60:61]
	s_mov_b32 m0, s66
	s_nop 0
	global_load_lds_dwordx4 v[194:195], off
	v_lshl_add_u64 v[194:195], v[234:235], 0, s[60:61]
	s_mov_b32 m0, s67
	s_nop 0
	global_load_lds_dwordx4 v[194:195], off
	s_waitcnt vmcnt(8)
	s_waitcnt lgkmcnt(0)
	s_barrier
	s_setprio 0
	s_waitcnt lgkmcnt(0)
	v_mfma_f32_16x16x32_bf16 v[62:65], v[148:151], v[182:185], v[62:65]
	v_mfma_f32_16x16x32_bf16 v[58:61], v[156:159], v[182:185], v[58:61]
	v_mfma_f32_16x16x32_bf16 v[54:57], v[148:151], v[210:213], v[54:57]
	v_mfma_f32_16x16x32_bf16 v[50:53], v[156:159], v[210:213], v[50:53]
	v_mfma_f32_16x16x32_bf16 v[46:49], v[148:151], v[218:221], v[46:49]
	v_mfma_f32_16x16x32_bf16 v[42:45], v[156:159], v[218:221], v[42:45]
	v_mfma_f32_16x16x32_bf16 v[38:41], v[148:151], v[240:243], v[38:41]
	v_mfma_f32_16x16x32_bf16 v[34:37], v[156:159], v[240:243], v[34:37]
	v_mfma_f32_16x16x32_bf16 v[62:65], v[152:155], v[206:209], v[62:65]
	v_mfma_f32_16x16x32_bf16 v[58:61], v[160:163], v[206:209], v[58:61]
	v_mfma_f32_16x16x32_bf16 v[54:57], v[152:155], v[214:217], v[54:57]
	v_mfma_f32_16x16x32_bf16 v[50:53], v[160:163], v[214:217], v[50:53]
	v_mfma_f32_16x16x32_bf16 v[46:49], v[152:155], v[236:239], v[46:49]
	v_mfma_f32_16x16x32_bf16 v[42:45], v[160:163], v[236:239], v[42:45]
	v_mfma_f32_16x16x32_bf16 v[38:41], v[152:155], v[244:247], v[38:41]
	v_mfma_f32_16x16x32_bf16 v[34:37], v[160:163], v[244:247], v[34:37]
	v_mfma_f32_16x16x32_bf16 v[30:33], v[166:169], v[182:185], v[30:33]
	v_mfma_f32_16x16x32_bf16 v[26:29], v[174:177], v[182:185], v[26:29]
	v_mfma_f32_16x16x32_bf16 v[22:25], v[166:169], v[210:213], v[22:25]
	v_mfma_f32_16x16x32_bf16 v[18:21], v[174:177], v[210:213], v[18:21]
	v_mfma_f32_16x16x32_bf16 v[14:17], v[166:169], v[218:221], v[14:17]
	v_mfma_f32_16x16x32_bf16 v[10:13], v[174:177], v[218:221], v[10:13]
	v_mfma_f32_16x16x32_bf16 v[6:9], v[166:169], v[240:243], v[6:9]
	v_mfma_f32_16x16x32_bf16 v[2:5], v[174:177], v[240:243], v[2:5]
	v_mfma_f32_16x16x32_bf16 v[30:33], v[170:173], v[206:209], v[30:33]
	v_mfma_f32_16x16x32_bf16 v[26:29], v[178:181], v[206:209], v[26:29]
	v_mfma_f32_16x16x32_bf16 v[22:25], v[170:173], v[214:217], v[22:25]
	v_mfma_f32_16x16x32_bf16 v[18:21], v[178:181], v[214:217], v[18:21]
	v_mfma_f32_16x16x32_bf16 v[14:17], v[170:173], v[236:239], v[14:17]
	v_mfma_f32_16x16x32_bf16 v[10:13], v[178:181], v[236:239], v[10:13]
	v_mfma_f32_16x16x32_bf16 v[6:9], v[170:173], v[244:247], v[6:9]
	v_mfma_f32_16x16x32_bf16 v[2:5], v[178:181], v[244:247], v[2:5]
	s_setprio 1
	s_barrier
	s_add_i32 s8, s8, 2
	s_add_u32 s46, s46, 0x100
	s_addc_u32 s47, s47, 0
	s_cmp_gt_u32 s8, 29
	s_cbranch_scc0 .LBB0_170
	s_setprio 0
	s_and_b64 vcc, exec, s[54:55]
	s_cbranch_vccz .LBB0_173
	s_barrier

; #define PG8_STAGE(bufoff, gbase, voff) do { _Pragma("unroll") for (int _i = 0; _i < 2; ++_i) \
;         __builtin_amdgcn_global_load_lds((const unsigned*)((const char*)(gbase) + (voff)[_i]), (PG8_LAS unsigned*)(lds + (bufoff) + ldsw + _i * 8192), 16, 0, 0); } while (0)
; #define PG8_LDA(dst, b, h) do { _Pragma("unroll") for (int m = 0; m < 4; ++m) _Pragma("unroll") for (int k = 0; k < 2; ++k) dst[m][k] = *(const PG8_LAS bf16x8*)(lds + PG8_SA(b, h) + aoff + m * 2048 + k * 1024); } while (0)
; #define PG8_LDB(dst, b, h) do { _Pragma("unroll") for (int n = 0; n < 2; ++n) _Pragma("unroll") for (int k = 0; k < 2; ++k) dst[n][k] = *(const PG8_LAS bf16x8*)(lds + PG8_SB(b, h) + boff + n * 2048 + k * 1024); } while (0)
; #define PG8_MMA(ai, bj, At, Bt) do { __builtin_amdgcn_s_setprio(1); _Pragma("unroll") for (int m = 0; m < 4; ++m) _Pragma("unroll") for (int n = 0; n < 2; ++n) _Pragma("unroll") for (int k = 0; k < 2; ++k) \
;         acc[ai][bj][m][n] = __builtin_amdgcn_mfma_f32_16x16x32_bf16(Bt[n][k], At[m][k], acc[ai][bj][m][n], 0, 0, 0); __builtin_amdgcn_s_setprio(0); } while (0)
; #define PG8_WAIT_V(n) asm volatile("s_waitcnt vmcnt(" #n ")" ::: "memory")
; #define PG8_WAIT_L(n) asm volatile("s_waitcnt lgkmcnt(" #n ")" ::: "memory")
; template <class Epi, class Sched, bool ALIGN_EPI = false, bool SP2 = false>
; __device__ __forceinline__ void gemm_phase(PG8_LAS unsigned char* lds, const Gemm g, const Sched& S, const Epi& E) {
;     ...
;             const bool last = (t == nt - 2);
;             const char* a1 = cA + (size_t)(t + 1) * kstep;
;             const char* a2 = last ? nA : cA + (size_t)(t + 2) * kstep; const char* b2 = last ? nB : cB + (size_t)(t + 2) * kstep;
;             const char* a3 = a2 + kstep; const char* b3 = b2 + kstep;
;             if (last && has_next) S.a_ready(nxt);
;             if constexpr (SP2) {
;             PG8_LDB(B0, 0, 0); PG8_LDB(B1, 0, 1); PG8_SCHED; PG8_LDA(At, 0, 0); PG8_STAGE(PG8_SA(1, 1), a1 + hstep, voffA);
;             PG8_WAIT_V(8); PG8_WAIT_L(0); PG8_BAR; PG8_MMA(0, 0, At, B0); PG8_MMA(0, 1, At, B1); PG8_BAR; PG8_SCHED;
;             PG8_LDA(At, 0, 1); PG8_STAGE(PG8_SB(0, 0), b2, voffB); PG8_STAGE(PG8_SB(0, 1), b2 + hstepB, voffB); PG8_STAGE(PG8_SA(0, 0), a2, voffA);
;             PG8_WAIT_V(8); PG8_WAIT_L(0); PG8_BAR; PG8_MMA(1, 0, At, B0); PG8_MMA(1, 1, At, B1); PG8_BAR; PG8_SCHED;
.LBB0_788:
	s_add_u32 s9, s68, 0xfffe0080
	s_addc_u32 s10, s69, -1
	s_add_i32 s11, 0, 0x10000
	s_cmp_eq_u32 s8, 4
	s_cselect_b32 s77, s36, s10
	s_cselect_b32 s76, s37, s9
	s_cselect_b32 s73, s4, s7
	s_cselect_b32 s72, s5, s6
	s_add_i32 s9, 0, 0x14000
	v_add_u32_e32 v54, s11, v193
	v_add_u32_e32 v150, s9, v193
	ds_read_b128 v[34:37], v54
	ds_read_b128 v[38:41], v54 offset:1024
	ds_read_b128 v[50:53], v54 offset:2048
	ds_read_b128 v[54:57], v54 offset:3072
	ds_read_b128 v[114:117], v150
	ds_read_b128 v[126:129], v150 offset:1024
	ds_read_b128 v[138:141], v150 offset:2048
	ds_read_b128 v[150:153], v150 offset:3072
	v_lshl_add_u64 v[184:185], s[68:69], 0, v[180:181]
	s_add_i32 m0, s66, 0xc000
	ds_read_b128 v[154:157], v217
	ds_read_b128 v[158:161], v217 offset:1024
	ds_read_b128 v[170:173], v217 offset:2048
	ds_read_b128 v[206:209], v217 offset:3072
	ds_read_b128 v[210:213], v217 offset:4096
	ds_read_b128 v[218:221], v217 offset:5120
	ds_read_b128 v[236:239], v217 offset:6144
	ds_read_b128 v[240:243], v217 offset:7168
	global_load_lds_dwordx4 v[184:185], off
	v_lshl_add_u64 v[184:185], s[68:69], 0, v[182:183]
	s_add_i32 m0, s66, 0xe000
	s_nop 0
	global_load_lds_dwordx4 v[184:185], off
	s_waitcnt vmcnt(8)
	s_waitcnt lgkmcnt(0)
	s_barrier
	s_setprio 0
	s_waitcnt lgkmcnt(0)
	v_mfma_f32_16x16x32_bf16 v[166:169], v[34:37], v[154:157], v[166:169]
	v_mfma_f32_16x16x32_bf16 v[162:165], v[50:53], v[154:157], v[162:165]
	v_mfma_f32_16x16x32_bf16 v[134:137], v[34:37], v[170:173], v[134:137]
	v_mfma_f32_16x16x32_bf16 v[130:133], v[50:53], v[170:173], v[130:133]
	v_mfma_f32_16x16x32_bf16 v[110:113], v[34:37], v[210:213], v[110:113]
	v_mfma_f32_16x16x32_bf16 v[106:109], v[50:53], v[210:213], v[106:109]
	v_mfma_f32_16x16x32_bf16 v[94:97], v[34:37], v[236:239], v[94:97]
	v_mfma_f32_16x16x32_bf16 v[90:93], v[50:53], v[236:239], v[90:93]
	v_mfma_f32_16x16x32_bf16 v[166:169], v[38:41], v[158:161], v[166:169]
	v_mfma_f32_16x16x32_bf16 v[162:165], v[54:57], v[158:161], v[162:165]
	v_mfma_f32_16x16x32_bf16 v[134:137], v[38:41], v[206:209], v[134:137]
	v_mfma_f32_16x16x32_bf16 v[130:133], v[54:57], v[206:209], v[130:133]
	v_mfma_f32_16x16x32_bf16 v[110:113], v[38:41], v[218:221], v[110:113]
	v_mfma_f32_16x16x32_bf16 v[106:109], v[54:57], v[218:221], v[106:109]
	v_mfma_f32_16x16x32_bf16 v[94:97], v[38:41], v[240:243], v[94:97]
	v_mfma_f32_16x16x32_bf16 v[90:93], v[54:57], v[240:243], v[90:93]
	v_mfma_f32_16x16x32_bf16 v[146:149], v[114:117], v[154:157], v[146:149]
	v_mfma_f32_16x16x32_bf16 v[142:145], v[138:141], v[154:157], v[142:145]
	v_mfma_f32_16x16x32_bf16 v[122:125], v[114:117], v[170:173], v[122:125]
	v_mfma_f32_16x16x32_bf16 v[118:121], v[138:141], v[170:173], v[118:121]
	v_mfma_f32_16x16x32_bf16 v[102:105], v[114:117], v[210:213], v[102:105]
	v_mfma_f32_16x16x32_bf16 v[98:101], v[138:141], v[210:213], v[98:101]
	v_mfma_f32_16x16x32_bf16 v[86:89], v[114:117], v[236:239], v[86:89]
	v_mfma_f32_16x16x32_bf16 v[82:85], v[138:141], v[236:239], v[82:85]
	v_mfma_f32_16x16x32_bf16 v[146:149], v[126:129], v[158:161], v[146:149]
	v_mfma_f32_16x16x32_bf16 v[142:145], v[150:153], v[158:161], v[142:145]
	v_mfma_f32_16x16x32_bf16 v[122:125], v[126:129], v[206:209], v[122:125]
	v_mfma_f32_16x16x32_bf16 v[118:121], v[150:153], v[206:209], v[118:121]
	v_mfma_f32_16x16x32_bf16 v[102:105], v[126:129], v[218:221], v[102:105]
	v_mfma_f32_16x16x32_bf16 v[98:101], v[150:153], v[218:221], v[98:101]
	v_mfma_f32_16x16x32_bf16 v[86:89], v[126:129], v[240:243], v[86:89]
	v_mfma_f32_16x16x32_bf16 v[82:85], v[150:153], v[240:243], v[82:85]
	s_setprio 1
	s_barrier
	s_add_i32 s10, s11, s25
	v_lshl_add_u64 v[184:185], s[72:73], 0, v[190:191]
	s_mov_b32 m0, s10
	ds_read_b128 v[154:157], v217 offset:16384
	ds_read_b128 v[158:161], v217 offset:17408
	ds_read_b128 v[170:173], v217 offset:18432
	ds_read_b128 v[206:209], v217 offset:19456
	ds_read_b128 v[210:213], v217 offset:20480
	ds_read_b128 v[218:221], v217 offset:21504
	ds_read_b128 v[236:239], v217 offset:22528
	ds_read_b128 v[240:243], v217 offset:23552
	global_load_lds_dwordx4 v[184:185], off
	s_add_i32 m0, s10, 0x2000
	s_add_u32 s10, s72, 0x8000
	v_lshl_add_u64 v[194:195], s[72:73], 0, v[174:175]
	s_addc_u32 s11, s73, 0
	s_add_i32 s9, s9, s25
	global_load_lds_dwordx4 v[194:195], off
	v_lshl_add_u64 v[196:197], s[10:11], 0, v[190:191]
	s_mov_b32 m0, s9
	v_lshl_add_u64 v[198:199], s[76:77], 0, v[176:177]
	global_load_lds_dwordx4 v[196:197], off
	v_lshl_add_u64 v[196:197], s[10:11], 0, v[174:175]
	s_add_i32 m0, s9, 0x2000
	s_nop 0
	global_load_lds_dwordx4 v[196:197], off
	v_lshl_add_u64 v[196:197], s[76:77], 0, v[178:179]
	s_mov_b32 m0, s66
	s_nop 0
	global_load_lds_dwordx4 v[196:197], off
	s_mov_b32 m0, s67
	s_nop 0
	global_load_lds_dwordx4 v[198:199], off
	s_waitcnt vmcnt(8)
	s_waitcnt lgkmcnt(0)
	s_barrier
; #define PG8_STAGE(bufoff, gbase, voff) do { _Pragma("unroll") for (int _i = 0; _i < 2; ++_i) \
;         __builtin_amdgcn_global_load_lds((const unsigned*)((const char*)(gbase) + (voff)[_i]), (PG8_LAS unsigned*)(lds + (bufoff) + ldsw + _i * 8192), 16, 0, 0); } while (0)
; #define PG8_LDA(dst, b, h) do { _Pragma("unroll") for (int m = 0; m < 4; ++m) _Pragma("unroll") for (int k = 0; k < 2; ++k) dst[m][k] = *(const PG8_LAS bf16x8*)(lds + PG8_SA(b, h) + aoff + m * 2048 + k * 1024); } while (0)
; #define PG8_LDB(dst, b, h) do { _Pragma("unroll") for (int n = 0; n < 2; ++n) _Pragma("unroll") for (int k = 0; k < 2; ++k) dst[n][k] = *(const PG8_LAS bf16x8*)(lds + PG8_SB(b, h) + boff + n * 2048 + k * 1024); } while (0)
; #define PG8_MMA(ai, bj, At, Bt) do { __builtin_amdgcn_s_setprio(1); _Pragma("unroll") for (int m = 0; m < 4; ++m) _Pragma("unroll") for (int n = 0; n < 2; ++n) _Pragma("unroll") for (int k = 0; k < 2; ++k) \
;         acc[ai][bj][m][n] = __builtin_amdgcn_mfma_f32_16x16x32_bf16(Bt[n][k], At[m][k], acc[ai][bj][m][n], 0, 0, 0); __builtin_amdgcn_s_setprio(0); } while (0)
; #define PG8_WAIT_V(n) asm volatile("s_waitcnt vmcnt(" #n ")" ::: "memory")
; #define PG8_WAIT_L(n) asm volatile("s_waitcnt lgkmcnt(" #n ")" ::: "memory")
; #define PG8_BAR __builtin_amdgcn_s_barrier()
; #define PG8_SCHED __builtin_amdgcn_sched_barrier(0)
; template <class Epi, class Sched, bool ALIGN_EPI = false, bool SP2 = false>
; __device__ __forceinline__ void gemm_phase(PG8_LAS unsigned char* lds, const Gemm g, const Sched& S, const Epi& E) {
;     ...
;             PG8_WAIT_V(8); PG8_WAIT_L(0); PG8_BAR; PG8_MMA(1, 0, At, B0); PG8_MMA(1, 1, At, B1); PG8_BAR; PG8_SCHED;
;             PG8_LDB(B0, 1, 0); PG8_LDB(B1, 1, 1); PG8_SCHED; PG8_LDA(At, 1, 0); PG8_STAGE(PG8_SA(0, 1), a2 + hstep, voffA);
;             PG8_WAIT_V(8); PG8_WAIT_L(0); PG8_BAR; PG8_MMA(0, 0, At, B0); PG8_MMA(0, 1, At, B1); PG8_BAR; PG8_SCHED;
	s_setprio 0
	s_waitcnt lgkmcnt(0)
	v_mfma_f32_16x16x32_bf16 v[78:81], v[34:37], v[154:157], v[78:81]
	v_mfma_f32_16x16x32_bf16 v[74:77], v[50:53], v[154:157], v[74:77]
	v_mfma_f32_16x16x32_bf16 v[62:65], v[34:37], v[170:173], v[62:65]
	v_mfma_f32_16x16x32_bf16 v[58:61], v[50:53], v[170:173], v[58:61]
	v_mfma_f32_16x16x32_bf16 v[30:33], v[34:37], v[210:213], v[30:33]
	v_mfma_f32_16x16x32_bf16 v[26:29], v[50:53], v[210:213], v[26:29]
	v_mfma_f32_16x16x32_bf16 v[14:17], v[34:37], v[236:239], v[14:17]
	v_mfma_f32_16x16x32_bf16 v[10:13], v[50:53], v[236:239], v[10:13]
	v_mfma_f32_16x16x32_bf16 v[78:81], v[38:41], v[158:161], v[78:81]
	v_mfma_f32_16x16x32_bf16 v[74:77], v[54:57], v[158:161], v[74:77]
	v_mfma_f32_16x16x32_bf16 v[62:65], v[38:41], v[206:209], v[62:65]
	v_mfma_f32_16x16x32_bf16 v[58:61], v[54:57], v[206:209], v[58:61]
	v_mfma_f32_16x16x32_bf16 v[30:33], v[38:41], v[218:221], v[30:33]
	v_mfma_f32_16x16x32_bf16 v[26:29], v[54:57], v[218:221], v[26:29]
	v_mfma_f32_16x16x32_bf16 v[14:17], v[38:41], v[240:243], v[14:17]
	v_mfma_f32_16x16x32_bf16 v[10:13], v[54:57], v[240:243], v[10:13]
	v_mfma_f32_16x16x32_bf16 v[46:49], v[114:117], v[170:173], v[46:49]
	v_mfma_f32_16x16x32_bf16 v[42:45], v[138:141], v[170:173], v[42:45]
	v_mfma_f32_16x16x32_bf16 v[22:25], v[114:117], v[210:213], v[22:25]
	v_mfma_f32_16x16x32_bf16 v[18:21], v[138:141], v[210:213], v[18:21]
	v_mfma_f32_16x16x32_bf16 v[6:9], v[114:117], v[236:239], v[6:9]
	v_mfma_f32_16x16x32_bf16 v[2:5], v[138:141], v[236:239], v[2:5]
	v_mfma_f32_16x16x32_bf16 v[34:37], v[114:117], v[154:157], v[70:73]
	v_mfma_f32_16x16x32_bf16 v[38:41], v[138:141], v[154:157], v[66:69]
	v_mfma_f32_16x16x32_bf16 v[46:49], v[126:129], v[206:209], v[46:49]
	v_mfma_f32_16x16x32_bf16 v[42:45], v[150:153], v[206:209], v[42:45]
	v_mfma_f32_16x16x32_bf16 v[22:25], v[126:129], v[218:221], v[22:25]
	v_mfma_f32_16x16x32_bf16 v[18:21], v[150:153], v[218:221], v[18:21]
	v_mfma_f32_16x16x32_bf16 v[6:9], v[126:129], v[240:243], v[6:9]
	v_mfma_f32_16x16x32_bf16 v[2:5], v[150:153], v[240:243], v[2:5]
	v_mfma_f32_16x16x32_bf16 v[34:37], v[126:129], v[158:161], v[34:37]
	v_mfma_f32_16x16x32_bf16 v[38:41], v[150:153], v[158:161], v[38:41]
	s_setprio 1
	s_barrier
	s_add_i32 s9, 0, 0x18000
	s_add_i32 s12, 0, 0x1c000
	v_add_u32_e32 v70, s9, v193
	v_add_u32_e32 v150, s12, v193
	ds_read_b128 v[50:53], v70
	ds_read_b128 v[54:57], v70 offset:1024
	ds_read_b128 v[66:69], v70 offset:2048
	ds_read_b128 v[70:73], v70 offset:3072
	ds_read_b128 v[114:117], v150
	ds_read_b128 v[126:129], v150 offset:1024
	ds_read_b128 v[138:141], v150 offset:2048
	ds_read_b128 v[150:153], v150 offset:3072
	s_add_u32 s10, s76, 0x20000
	s_addc_u32 s11, s77, 0
	s_mov_b32 m0, s80
	v_lshl_add_u64 v[214:215], s[10:11], 0, v[178:179]
	ds_read_b128 v[154:157], v217 offset:32768
	ds_read_b128 v[158:161], v217 offset:33792
	ds_read_b128 v[170:173], v217 offset:34816
	ds_read_b128 v[206:209], v217 offset:35840
	ds_read_b128 v[210:213], v217 offset:36864
	ds_read_b128 v[218:221], v217 offset:37888
	ds_read_b128 v[236:239], v217 offset:38912
	ds_read_b128 v[240:243], v217 offset:39936
	global_load_lds_dwordx4 v[214:215], off
	v_lshl_add_u64 v[214:215], s[10:11], 0, v[176:177]
	s_mov_b32 m0, s81
	s_nop 0
	global_load_lds_dwordx4 v[214:215], off
	s_waitcnt vmcnt(8)
	s_waitcnt lgkmcnt(0)
	s_barrier
	s_setprio 0
	s_waitcnt lgkmcnt(0)
	v_mfma_f32_16x16x32_bf16 v[166:169], v[50:53], v[154:157], v[166:169]
	v_mfma_f32_16x16x32_bf16 v[162:165], v[66:69], v[154:157], v[162:165]
	v_mfma_f32_16x16x32_bf16 v[134:137], v[50:53], v[170:173], v[134:137]
	v_mfma_f32_16x16x32_bf16 v[130:133], v[66:69], v[170:173], v[130:133]
	v_mfma_f32_16x16x32_bf16 v[110:113], v[50:53], v[210:213], v[110:113]
	v_mfma_f32_16x16x32_bf16 v[106:109], v[66:69], v[210:213], v[106:109]
	v_mfma_f32_16x16x32_bf16 v[94:97], v[50:53], v[236:239], v[94:97]
	v_mfma_f32_16x16x32_bf16 v[90:93], v[66:69], v[236:239], v[90:93]
	v_mfma_f32_16x16x32_bf16 v[166:169], v[54:57], v[158:161], v[166:169]
	v_mfma_f32_16x16x32_bf16 v[162:165], v[70:73], v[158:161], v[162:165]
	v_mfma_f32_16x16x32_bf16 v[134:137], v[54:57], v[206:209], v[134:137]
	v_mfma_f32_16x16x32_bf16 v[130:133], v[70:73], v[206:209], v[130:133]
	v_mfma_f32_16x16x32_bf16 v[110:113], v[54:57], v[218:221], v[110:113]
	v_mfma_f32_16x16x32_bf16 v[106:109], v[70:73], v[218:221], v[106:109]
	v_mfma_f32_16x16x32_bf16 v[94:97], v[54:57], v[240:243], v[94:97]
	v_mfma_f32_16x16x32_bf16 v[90:93], v[70:73], v[240:243], v[90:93]
	v_mfma_f32_16x16x32_bf16 v[146:149], v[114:117], v[154:157], v[146:149]
	v_mfma_f32_16x16x32_bf16 v[142:145], v[138:141], v[154:157], v[142:145]
	v_mfma_f32_16x16x32_bf16 v[122:125], v[114:117], v[170:173], v[122:125]
	v_mfma_f32_16x16x32_bf16 v[118:121], v[138:141], v[170:173], v[118:121]
	v_mfma_f32_16x16x32_bf16 v[102:105], v[114:117], v[210:213], v[102:105]
	v_mfma_f32_16x16x32_bf16 v[98:101], v[138:141], v[210:213], v[98:101]
	v_mfma_f32_16x16x32_bf16 v[86:89], v[114:117], v[236:239], v[86:89]
	v_mfma_f32_16x16x32_bf16 v[82:85], v[138:141], v[236:239], v[82:85]
	v_mfma_f32_16x16x32_bf16 v[146:149], v[126:129], v[158:161], v[146:149]
	v_mfma_f32_16x16x32_bf16 v[142:145], v[150:153], v[158:161], v[142:145]
	v_mfma_f32_16x16x32_bf16 v[122:125], v[126:129], v[206:209], v[122:125]
	v_mfma_f32_16x16x32_bf16 v[118:121], v[150:153], v[206:209], v[118:121]
	v_mfma_f32_16x16x32_bf16 v[102:105], v[126:129], v[218:221], v[102:105]
	v_mfma_f32_16x16x32_bf16 v[98:101], v[150:153], v[218:221], v[98:101]
	v_mfma_f32_16x16x32_bf16 v[86:89], v[126:129], v[240:243], v[86:89]
	v_mfma_f32_16x16x32_bf16 v[82:85], v[150:153], v[240:243], v[82:85]
	s_setprio 1
	s_barrier
; #define PG8_STAGE(bufoff, gbase, voff) do { _Pragma("unroll") for (int _i = 0; _i < 2; ++_i) \
;         __builtin_amdgcn_global_load_lds((const unsigned*)((const char*)(gbase) + (voff)[_i]), (PG8_LAS unsigned*)(lds + (bufoff) + ldsw + _i * 8192), 16, 0, 0); } while (0)
; #define PG8_LDA(dst, b, h) do { _Pragma("unroll") for (int m = 0; m < 4; ++m) _Pragma("unroll") for (int k = 0; k < 2; ++k) dst[m][k] = *(const PG8_LAS bf16x8*)(lds + PG8_SA(b, h) + aoff + m * 2048 + k * 1024); } while (0)
; #define PG8_MMA(ai, bj, At, Bt) do { __builtin_amdgcn_s_setprio(1); _Pragma("unroll") for (int m = 0; m < 4; ++m) _Pragma("unroll") for (int n = 0; n < 2; ++n) _Pragma("unroll") for (int k = 0; k < 2; ++k) \
;         acc[ai][bj][m][n] = __builtin_amdgcn_mfma_f32_16x16x32_bf16(Bt[n][k], At[m][k], acc[ai][bj][m][n], 0, 0, 0); __builtin_amdgcn_s_setprio(0); } while (0)
; #define PG8_WAIT_V(n) asm volatile("s_waitcnt vmcnt(" #n ")" ::: "memory")
; #define PG8_WAIT_L(n) asm volatile("s_waitcnt lgkmcnt(" #n ")" ::: "memory")
; #define PG8_BAR __builtin_amdgcn_s_barrier()
; #define PG8_SCHED __builtin_amdgcn_sched_barrier(0)
; template <class Epi, class Sched, bool ALIGN_EPI = false, bool SP2 = false>
; __device__ __forceinline__ void gemm_phase(PG8_LAS unsigned char* lds, const Gemm g, const Sched& S, const Epi& E) {
;     ...
;             PG8_LDA(At, 1, 1); PG8_STAGE(PG8_SB(1, 0), b3, voffB); PG8_STAGE(PG8_SB(1, 1), b3 + hstepB, voffB); PG8_STAGE(PG8_SA(1, 0), a3, voffA);
;             PG8_WAIT_V(8); PG8_WAIT_L(0); PG8_BAR; PG8_MMA(1, 0, At, B0); PG8_MMA(1, 1, At, B1); PG8_BAR; PG8_SCHED;
	s_add_i32 s9, s9, s25
	v_lshl_add_u64 v[184:185], v[184:185], 0, s[60:61]
	s_mov_b32 m0, s9
	ds_read_b128 v[154:157], v217 offset:49152
	ds_read_b128 v[158:161], v217 offset:50176
	ds_read_b128 v[170:173], v217 offset:51200
	ds_read_b128 v[206:209], v217 offset:52224
	ds_read_b128 v[210:213], v217 offset:53248
	ds_read_b128 v[218:221], v217 offset:54272
	ds_read_b128 v[236:239], v217 offset:55296
	ds_read_b128 v[240:243], v217 offset:56320
	global_load_lds_dwordx4 v[184:185], off
	s_add_i32 m0, s9, 0x2000
	s_add_u32 s10, s72, 0x8080
	v_lshl_add_u64 v[184:185], v[194:195], 0, s[60:61]
	s_addc_u32 s11, s73, 0
	s_add_i32 s9, s12, s25
	global_load_lds_dwordx4 v[184:185], off
	v_lshl_add_u64 v[184:185], s[10:11], 0, v[190:191]
	s_mov_b32 m0, s9
	s_nop 0
	global_load_lds_dwordx4 v[184:185], off
	v_lshl_add_u64 v[184:185], s[10:11], 0, v[174:175]
	s_add_i32 m0, s9, 0x2000
	s_nop 0
	global_load_lds_dwordx4 v[184:185], off
	v_lshl_add_u64 v[184:185], v[196:197], 0, s[60:61]
	s_mov_b32 m0, s82
	s_nop 0
	global_load_lds_dwordx4 v[184:185], off
	v_lshl_add_u64 v[184:185], v[198:199], 0, s[60:61]
	s_mov_b32 m0, s92
	s_nop 0
	global_load_lds_dwordx4 v[184:185], off
	s_waitcnt vmcnt(8)
	s_waitcnt lgkmcnt(0)
	s_barrier
	s_setprio 0
	s_waitcnt lgkmcnt(0)
	v_mfma_f32_16x16x32_bf16 v[78:81], v[50:53], v[154:157], v[78:81]
	v_mfma_f32_16x16x32_bf16 v[74:77], v[66:69], v[154:157], v[74:77]
	v_mfma_f32_16x16x32_bf16 v[62:65], v[50:53], v[170:173], v[62:65]
	v_mfma_f32_16x16x32_bf16 v[58:61], v[66:69], v[170:173], v[58:61]
	v_mfma_f32_16x16x32_bf16 v[30:33], v[50:53], v[210:213], v[30:33]
	v_mfma_f32_16x16x32_bf16 v[26:29], v[66:69], v[210:213], v[26:29]
	v_mfma_f32_16x16x32_bf16 v[14:17], v[50:53], v[236:239], v[14:17]
	v_mfma_f32_16x16x32_bf16 v[10:13], v[66:69], v[236:239], v[10:13]
	v_mfma_f32_16x16x32_bf16 v[78:81], v[54:57], v[158:161], v[78:81]
	v_mfma_f32_16x16x32_bf16 v[74:77], v[70:73], v[158:161], v[74:77]
	v_mfma_f32_16x16x32_bf16 v[62:65], v[54:57], v[206:209], v[62:65]
	v_mfma_f32_16x16x32_bf16 v[58:61], v[70:73], v[206:209], v[58:61]
	v_mfma_f32_16x16x32_bf16 v[30:33], v[54:57], v[218:221], v[30:33]
	v_mfma_f32_16x16x32_bf16 v[26:29], v[70:73], v[218:221], v[26:29]
	v_mfma_f32_16x16x32_bf16 v[14:17], v[54:57], v[240:243], v[14:17]
	v_mfma_f32_16x16x32_bf16 v[10:13], v[70:73], v[240:243], v[10:13]
	v_mfma_f32_16x16x32_bf16 v[34:37], v[114:117], v[154:157], v[34:37]
	v_mfma_f32_16x16x32_bf16 v[70:73], v[126:129], v[158:161], v[34:37]
	v_mfma_f32_16x16x32_bf16 v[34:37], v[138:141], v[154:157], v[38:41]
	v_mfma_f32_16x16x32_bf16 v[66:69], v[150:153], v[158:161], v[34:37]
	v_mfma_f32_16x16x32_bf16 v[34:37], v[114:117], v[170:173], v[46:49]
	v_mfma_f32_16x16x32_bf16 v[46:49], v[126:129], v[206:209], v[34:37]
	v_mfma_f32_16x16x32_bf16 v[34:37], v[138:141], v[170:173], v[42:45]
	v_mfma_f32_16x16x32_bf16 v[22:25], v[114:117], v[210:213], v[22:25]
	v_mfma_f32_16x16x32_bf16 v[18:21], v[138:141], v[210:213], v[18:21]
	v_mfma_f32_16x16x32_bf16 v[6:9], v[114:117], v[236:239], v[6:9]
	v_mfma_f32_16x16x32_bf16 v[2:5], v[138:141], v[236:239], v[2:5]
	v_mfma_f32_16x16x32_bf16 v[42:45], v[150:153], v[206:209], v[34:37]
	v_mfma_f32_16x16x32_bf16 v[22:25], v[126:129], v[218:221], v[22:25]
	v_mfma_f32_16x16x32_bf16 v[18:21], v[150:153], v[218:221], v[18:21]
	v_mfma_f32_16x16x32_bf16 v[6:9], v[126:129], v[240:243], v[6:9]
	v_mfma_f32_16x16x32_bf16 v[2:5], v[150:153], v[240:243], v[2:5]
	s_setprio 1
	s_barrier
	s_add_i32 s8, s8, 2
	s_add_u32 s68, s68, 0x100
	s_addc_u32 s69, s69, 0
	s_add_u32 s6, s6, 0x100
	s_addc_u32 s7, s7, 0
	s_cmp_gt_u32 s8, 5
	s_cbranch_scc0 .LBB0_788
	s_setprio 0
	s_and_b64 vcc, exec, s[46:47]
	s_cbranch_vccz .LBB0_791
	s_barrier

; #define PG8_STAGE(bufoff, gbase, voff) do { _Pragma("unroll") for (int _i = 0; _i < 2; ++_i) \
;         __builtin_amdgcn_global_load_lds((const unsigned*)((const char*)(gbase) + (voff)[_i]), (PG8_LAS unsigned*)(lds + (bufoff) + ldsw + _i * 8192), 16, 0, 0); } while (0)
; #define PG8_LDA(dst, b, h) do { _Pragma("unroll") for (int m = 0; m < 4; ++m) _Pragma("unroll") for (int k = 0; k < 2; ++k) dst[m][k] = *(const PG8_LAS bf16x8*)(lds + PG8_SA(b, h) + aoff + m * 2048 + k * 1024); } while (0)
; #define PG8_LDB(dst, b, h) do { _Pragma("unroll") for (int n = 0; n < 2; ++n) _Pragma("unroll") for (int k = 0; k < 2; ++k) dst[n][k] = *(const PG8_LAS bf16x8*)(lds + PG8_SB(b, h) + boff + n * 2048 + k * 1024); } while (0)
; #define PG8_MMA(ai, bj, At, Bt) do { __builtin_amdgcn_s_setprio(1); _Pragma("unroll") for (int m = 0; m < 4; ++m) _Pragma("unroll") for (int n = 0; n < 2; ++n) _Pragma("unroll") for (int k = 0; k < 2; ++k) \
;         acc[ai][bj][m][n] = __builtin_amdgcn_mfma_f32_16x16x32_bf16(Bt[n][k], At[m][k], acc[ai][bj][m][n], 0, 0, 0); __builtin_amdgcn_s_setprio(0); } while (0)
; #define PG8_WAIT_V(n) asm volatile("s_waitcnt vmcnt(" #n ")" ::: "memory")
; #define PG8_WAIT_L(n) asm volatile("s_waitcnt lgkmcnt(" #n ")" ::: "memory")
; template <class Epi, class Sched, bool ALIGN_EPI = false, bool SP2 = false>
; __device__ __forceinline__ void gemm_phase(PG8_LAS unsigned char* lds, const Gemm g, const Sched& S, const Epi& E) {
;     ...
;             const bool last = (t == nt - 2);
;             const char* a1 = cA + (size_t)(t + 1) * kstep;
;             const char* a2 = last ? nA : cA + (size_t)(t + 2) * kstep; const char* b2 = last ? nB : cB + (size_t)(t + 2) * kstep;
;             const char* a3 = a2 + kstep; const char* b3 = b2 + kstep;
;             if (last && has_next) S.a_ready(nxt);
;             if constexpr (SP2) {
;             PG8_LDB(B0, 0, 0); PG8_LDB(B1, 0, 1); PG8_SCHED; PG8_LDA(At, 0, 0); PG8_STAGE(PG8_SA(1, 1), a1 + hstep, voffA);
;             PG8_WAIT_V(8); PG8_WAIT_L(0); PG8_BAR; PG8_MMA(0, 0, At, B0); PG8_MMA(0, 1, At, B1); PG8_BAR; PG8_SCHED;
;             PG8_LDA(At, 0, 1); PG8_STAGE(PG8_SB(0, 0), b2, voffB); PG8_STAGE(PG8_SB(0, 1), b2 + hstepB, voffB); PG8_STAGE(PG8_SA(0, 0), a2, voffA);
;             PG8_WAIT_V(8); PG8_WAIT_L(0); PG8_BAR; PG8_MMA(1, 0, At, B0); PG8_MMA(1, 1, At, B1); PG8_BAR; PG8_SCHED;
.LBB0_927:
	s_add_u32 s9, s38, 0xfff80080
	s_addc_u32 s10, s39, -1
	s_add_i32 s11, 0, 0x10000
	s_cmp_eq_u32 s8, 28
	s_cselect_b32 s95, s36, s10
	s_cselect_b32 s94, s37, s9
	s_cselect_b32 s47, s4, s7
	s_cselect_b32 s46, s5, s6
	s_add_i32 s9, 0, 0x14000
	v_add_u32_e32 v86, s11, v193
	v_add_u32_e32 v158, s9, v193
	ds_read_b128 v[66:69], v86
	ds_read_b128 v[70:73], v86 offset:1024
	ds_read_b128 v[78:81], v86 offset:2048
	ds_read_b128 v[86:89], v86 offset:3072
	ds_read_b128 v[146:149], v158
	ds_read_b128 v[150:153], v158 offset:1024
	ds_read_b128 v[154:157], v158 offset:2048
	ds_read_b128 v[158:161], v158 offset:3072
	v_lshl_add_u64 v[194:195], s[38:39], 0, v[212:213]
	s_add_i32 m0, s66, 0xc000
	ds_read_b128 v[162:165], v236
	ds_read_b128 v[166:169], v236 offset:1024
	ds_read_b128 v[170:173], v236 offset:2048
	ds_read_b128 v[174:177], v236 offset:3072
	ds_read_b128 v[178:181], v236 offset:4096
	ds_read_b128 v[182:185], v236 offset:5120
	ds_read_b128 v[216:219], v236 offset:6144
	ds_read_b128 v[220:223], v236 offset:7168
	global_load_lds_dwordx4 v[194:195], off
	v_lshl_add_u64 v[194:195], s[38:39], 0, v[214:215]
	s_add_i32 m0, s66, 0xe000
	s_nop 0
	global_load_lds_dwordx4 v[194:195], off
	s_waitcnt vmcnt(8)
	s_waitcnt lgkmcnt(0)
	s_barrier
	s_setprio 0
	s_waitcnt lgkmcnt(0)
	v_mfma_f32_16x16x32_bf16 v[142:145], v[66:69], v[162:165], v[142:145]
	v_mfma_f32_16x16x32_bf16 v[138:141], v[78:81], v[162:165], v[138:141]
	v_mfma_f32_16x16x32_bf16 v[126:129], v[66:69], v[170:173], v[126:129]
	v_mfma_f32_16x16x32_bf16 v[122:125], v[78:81], v[170:173], v[122:125]
	v_mfma_f32_16x16x32_bf16 v[110:113], v[66:69], v[178:181], v[110:113]
	v_mfma_f32_16x16x32_bf16 v[106:109], v[78:81], v[178:181], v[106:109]
	v_mfma_f32_16x16x32_bf16 v[94:97], v[66:69], v[216:219], v[94:97]
	v_mfma_f32_16x16x32_bf16 v[90:93], v[78:81], v[216:219], v[90:93]
	v_mfma_f32_16x16x32_bf16 v[142:145], v[70:73], v[166:169], v[142:145]
	v_mfma_f32_16x16x32_bf16 v[138:141], v[86:89], v[166:169], v[138:141]
	v_mfma_f32_16x16x32_bf16 v[126:129], v[70:73], v[174:177], v[126:129]
	v_mfma_f32_16x16x32_bf16 v[122:125], v[86:89], v[174:177], v[122:125]
	v_mfma_f32_16x16x32_bf16 v[110:113], v[70:73], v[182:185], v[110:113]
	v_mfma_f32_16x16x32_bf16 v[106:109], v[86:89], v[182:185], v[106:109]
	v_mfma_f32_16x16x32_bf16 v[94:97], v[70:73], v[220:223], v[94:97]
	v_mfma_f32_16x16x32_bf16 v[90:93], v[86:89], v[220:223], v[90:93]
	v_mfma_f32_16x16x32_bf16 v[134:137], v[146:149], v[162:165], v[134:137]
	v_mfma_f32_16x16x32_bf16 v[130:133], v[154:157], v[162:165], v[130:133]
	v_mfma_f32_16x16x32_bf16 v[118:121], v[146:149], v[170:173], v[118:121]
	v_mfma_f32_16x16x32_bf16 v[114:117], v[154:157], v[170:173], v[114:117]
	v_mfma_f32_16x16x32_bf16 v[102:105], v[146:149], v[178:181], v[102:105]
	v_mfma_f32_16x16x32_bf16 v[98:101], v[154:157], v[178:181], v[98:101]
	v_mfma_f32_16x16x32_bf16 v[82:85], v[146:149], v[216:219], v[82:85]
	v_mfma_f32_16x16x32_bf16 v[74:77], v[154:157], v[216:219], v[74:77]
	v_mfma_f32_16x16x32_bf16 v[134:137], v[150:153], v[166:169], v[134:137]
	v_mfma_f32_16x16x32_bf16 v[130:133], v[158:161], v[166:169], v[130:133]
	v_mfma_f32_16x16x32_bf16 v[118:121], v[150:153], v[174:177], v[118:121]
	v_mfma_f32_16x16x32_bf16 v[114:117], v[158:161], v[174:177], v[114:117]
	v_mfma_f32_16x16x32_bf16 v[102:105], v[150:153], v[182:185], v[102:105]
	v_mfma_f32_16x16x32_bf16 v[98:101], v[158:161], v[182:185], v[98:101]
	v_mfma_f32_16x16x32_bf16 v[82:85], v[150:153], v[220:223], v[82:85]
	v_mfma_f32_16x16x32_bf16 v[74:77], v[158:161], v[220:223], v[74:77]
	s_setprio 1
	s_barrier
	s_add_i32 s10, s11, s25
	v_lshl_add_u64 v[194:195], s[46:47], 0, v[190:191]
	s_mov_b32 m0, s10
	ds_read_b128 v[162:165], v236 offset:16384
	ds_read_b128 v[166:169], v236 offset:17408
	ds_read_b128 v[170:173], v236 offset:18432
	ds_read_b128 v[174:177], v236 offset:19456
	ds_read_b128 v[178:181], v236 offset:20480
	ds_read_b128 v[182:185], v236 offset:21504
	ds_read_b128 v[216:219], v236 offset:22528
	ds_read_b128 v[220:223], v236 offset:23552
	global_load_lds_dwordx4 v[194:195], off
	s_add_i32 m0, s10, 0x2000
	s_add_u32 s10, s46, 0x20000
	v_lshl_add_u64 v[196:197], s[46:47], 0, v[206:207]
	s_addc_u32 s11, s47, 0
	s_add_i32 s9, s9, s25
	global_load_lds_dwordx4 v[196:197], off
	v_lshl_add_u64 v[198:199], s[10:11], 0, v[190:191]
	s_mov_b32 m0, s9
	v_lshl_add_u64 v[238:239], s[94:95], 0, v[208:209]
	global_load_lds_dwordx4 v[198:199], off
	v_lshl_add_u64 v[198:199], s[10:11], 0, v[206:207]
	s_add_i32 m0, s9, 0x2000
	s_nop 0
	global_load_lds_dwordx4 v[198:199], off
	v_lshl_add_u64 v[198:199], s[94:95], 0, v[210:211]
	s_mov_b32 m0, s66
	s_nop 0
	global_load_lds_dwordx4 v[198:199], off
	s_mov_b32 m0, s67
	s_nop 0
	global_load_lds_dwordx4 v[238:239], off
	s_waitcnt vmcnt(8)
	s_waitcnt lgkmcnt(0)
	s_barrier
; #define PG8_STAGE(bufoff, gbase, voff) do { _Pragma("unroll") for (int _i = 0; _i < 2; ++_i) \
;         __builtin_amdgcn_global_load_lds((const unsigned*)((const char*)(gbase) + (voff)[_i]), (PG8_LAS unsigned*)(lds + (bufoff) + ldsw + _i * 8192), 16, 0, 0); } while (0)
; #define PG8_LDA(dst, b, h) do { _Pragma("unroll") for (int m = 0; m < 4; ++m) _Pragma("unroll") for (int k = 0; k < 2; ++k) dst[m][k] = *(const PG8_LAS bf16x8*)(lds + PG8_SA(b, h) + aoff + m * 2048 + k * 1024); } while (0)
; #define PG8_LDB(dst, b, h) do { _Pragma("unroll") for (int n = 0; n < 2; ++n) _Pragma("unroll") for (int k = 0; k < 2; ++k) dst[n][k] = *(const PG8_LAS bf16x8*)(lds + PG8_SB(b, h) + boff + n * 2048 + k * 1024); } while (0)
; #define PG8_MMA(ai, bj, At, Bt) do { __builtin_amdgcn_s_setprio(1); _Pragma("unroll") for (int m = 0; m < 4; ++m) _Pragma("unroll") for (int n = 0; n < 2; ++n) _Pragma("unroll") for (int k = 0; k < 2; ++k) \
;         acc[ai][bj][m][n] = __builtin_amdgcn_mfma_f32_16x16x32_bf16(Bt[n][k], At[m][k], acc[ai][bj][m][n], 0, 0, 0); __builtin_amdgcn_s_setprio(0); } while (0)
; #define PG8_WAIT_V(n) asm volatile("s_waitcnt vmcnt(" #n ")" ::: "memory")
; #define PG8_WAIT_L(n) asm volatile("s_waitcnt lgkmcnt(" #n ")" ::: "memory")
; #define PG8_BAR __builtin_amdgcn_s_barrier()
; #define PG8_SCHED __builtin_amdgcn_sched_barrier(0)
; template <class Epi, class Sched, bool ALIGN_EPI = false, bool SP2 = false>
; __device__ __forceinline__ void gemm_phase(PG8_LAS unsigned char* lds, const Gemm g, const Sched& S, const Epi& E) {
;     ...
;             PG8_WAIT_V(8); PG8_WAIT_L(0); PG8_BAR; PG8_MMA(1, 0, At, B0); PG8_MMA(1, 1, At, B1); PG8_BAR; PG8_SCHED;
;             PG8_LDB(B0, 1, 0); PG8_LDB(B1, 1, 1); PG8_SCHED; PG8_LDA(At, 1, 0); PG8_STAGE(PG8_SA(0, 1), a2 + hstep, voffA);
;             PG8_WAIT_V(8); PG8_WAIT_L(0); PG8_BAR; PG8_MMA(0, 0, At, B0); PG8_MMA(0, 1, At, B1); PG8_BAR; PG8_SCHED;
	s_setprio 0
	s_waitcnt lgkmcnt(0)
	v_mfma_f32_16x16x32_bf16 v[62:65], v[66:69], v[162:165], v[62:65]
	v_mfma_f32_16x16x32_bf16 v[58:61], v[78:81], v[162:165], v[58:61]
	v_mfma_f32_16x16x32_bf16 v[46:49], v[66:69], v[170:173], v[46:49]
	v_mfma_f32_16x16x32_bf16 v[42:45], v[78:81], v[170:173], v[42:45]
	v_mfma_f32_16x16x32_bf16 v[30:33], v[66:69], v[178:181], v[30:33]
	v_mfma_f32_16x16x32_bf16 v[26:29], v[78:81], v[178:181], v[26:29]
	v_mfma_f32_16x16x32_bf16 v[14:17], v[66:69], v[216:219], v[14:17]
	v_mfma_f32_16x16x32_bf16 v[10:13], v[78:81], v[216:219], v[10:13]
	v_mfma_f32_16x16x32_bf16 v[62:65], v[70:73], v[166:169], v[62:65]
	v_mfma_f32_16x16x32_bf16 v[58:61], v[86:89], v[166:169], v[58:61]
	v_mfma_f32_16x16x32_bf16 v[46:49], v[70:73], v[174:177], v[46:49]
	v_mfma_f32_16x16x32_bf16 v[42:45], v[86:89], v[174:177], v[42:45]
	v_mfma_f32_16x16x32_bf16 v[30:33], v[70:73], v[182:185], v[30:33]
	v_mfma_f32_16x16x32_bf16 v[26:29], v[86:89], v[182:185], v[26:29]
	v_mfma_f32_16x16x32_bf16 v[14:17], v[70:73], v[220:223], v[14:17]
	v_mfma_f32_16x16x32_bf16 v[10:13], v[86:89], v[220:223], v[10:13]
	v_mfma_f32_16x16x32_bf16 v[54:57], v[146:149], v[162:165], v[54:57]
	v_mfma_f32_16x16x32_bf16 v[50:53], v[154:157], v[162:165], v[50:53]
	v_mfma_f32_16x16x32_bf16 v[38:41], v[146:149], v[170:173], v[38:41]
	v_mfma_f32_16x16x32_bf16 v[34:37], v[154:157], v[170:173], v[34:37]
	v_mfma_f32_16x16x32_bf16 v[22:25], v[146:149], v[178:181], v[22:25]
	v_mfma_f32_16x16x32_bf16 v[18:21], v[154:157], v[178:181], v[18:21]
	v_mfma_f32_16x16x32_bf16 v[6:9], v[146:149], v[216:219], v[6:9]
	v_mfma_f32_16x16x32_bf16 v[2:5], v[154:157], v[216:219], v[2:5]
	v_mfma_f32_16x16x32_bf16 v[54:57], v[150:153], v[166:169], v[54:57]
	v_mfma_f32_16x16x32_bf16 v[50:53], v[158:161], v[166:169], v[50:53]
	v_mfma_f32_16x16x32_bf16 v[38:41], v[150:153], v[174:177], v[38:41]
	v_mfma_f32_16x16x32_bf16 v[34:37], v[158:161], v[174:177], v[34:37]
	v_mfma_f32_16x16x32_bf16 v[22:25], v[150:153], v[182:185], v[22:25]
	v_mfma_f32_16x16x32_bf16 v[18:21], v[158:161], v[182:185], v[18:21]
	v_mfma_f32_16x16x32_bf16 v[6:9], v[150:153], v[220:223], v[6:9]
	v_mfma_f32_16x16x32_bf16 v[2:5], v[158:161], v[220:223], v[2:5]
	s_setprio 1
	s_barrier
	s_add_i32 s9, 0, 0x18000
	s_add_i32 s12, 0, 0x1c000
	v_add_u32_e32 v86, s9, v193
	v_add_u32_e32 v158, s12, v193
	ds_read_b128 v[66:69], v86
	ds_read_b128 v[70:73], v86 offset:1024
	ds_read_b128 v[78:81], v86 offset:2048
	ds_read_b128 v[86:89], v86 offset:3072
	ds_read_b128 v[146:149], v158
	ds_read_b128 v[150:153], v158 offset:1024
	ds_read_b128 v[154:157], v158 offset:2048
	ds_read_b128 v[158:161], v158 offset:3072
	s_add_u32 s10, s94, 0x80000
	s_addc_u32 s11, s95, 0
	s_mov_b32 m0, s59
	v_lshl_add_u64 v[240:241], s[10:11], 0, v[210:211]
	ds_read_b128 v[162:165], v236 offset:32768
	ds_read_b128 v[166:169], v236 offset:33792
	ds_read_b128 v[170:173], v236 offset:34816
	ds_read_b128 v[174:177], v236 offset:35840
	ds_read_b128 v[178:181], v236 offset:36864
	ds_read_b128 v[182:185], v236 offset:37888
	ds_read_b128 v[216:219], v236 offset:38912
	ds_read_b128 v[220:223], v236 offset:39936
	global_load_lds_dwordx4 v[240:241], off
	v_lshl_add_u64 v[240:241], s[10:11], 0, v[208:209]
	s_mov_b32 m0, s74
	s_nop 0
	global_load_lds_dwordx4 v[240:241], off
	s_waitcnt vmcnt(8)
	s_waitcnt lgkmcnt(0)
	s_barrier
	s_setprio 0
	s_waitcnt lgkmcnt(0)
	v_mfma_f32_16x16x32_bf16 v[142:145], v[66:69], v[162:165], v[142:145]
	v_mfma_f32_16x16x32_bf16 v[138:141], v[78:81], v[162:165], v[138:141]
	v_mfma_f32_16x16x32_bf16 v[126:129], v[66:69], v[170:173], v[126:129]
	v_mfma_f32_16x16x32_bf16 v[122:125], v[78:81], v[170:173], v[122:125]
	v_mfma_f32_16x16x32_bf16 v[110:113], v[66:69], v[178:181], v[110:113]
	v_mfma_f32_16x16x32_bf16 v[106:109], v[78:81], v[178:181], v[106:109]
	v_mfma_f32_16x16x32_bf16 v[94:97], v[66:69], v[216:219], v[94:97]
	v_mfma_f32_16x16x32_bf16 v[90:93], v[78:81], v[216:219], v[90:93]
	v_mfma_f32_16x16x32_bf16 v[142:145], v[70:73], v[166:169], v[142:145]
	v_mfma_f32_16x16x32_bf16 v[138:141], v[86:89], v[166:169], v[138:141]
	v_mfma_f32_16x16x32_bf16 v[126:129], v[70:73], v[174:177], v[126:129]
	v_mfma_f32_16x16x32_bf16 v[122:125], v[86:89], v[174:177], v[122:125]
	v_mfma_f32_16x16x32_bf16 v[110:113], v[70:73], v[182:185], v[110:113]
	v_mfma_f32_16x16x32_bf16 v[106:109], v[86:89], v[182:185], v[106:109]
	v_mfma_f32_16x16x32_bf16 v[94:97], v[70:73], v[220:223], v[94:97]
	v_mfma_f32_16x16x32_bf16 v[90:93], v[86:89], v[220:223], v[90:93]
	v_mfma_f32_16x16x32_bf16 v[134:137], v[146:149], v[162:165], v[134:137]
	v_mfma_f32_16x16x32_bf16 v[130:133], v[154:157], v[162:165], v[130:133]
	v_mfma_f32_16x16x32_bf16 v[118:121], v[146:149], v[170:173], v[118:121]
	v_mfma_f32_16x16x32_bf16 v[114:117], v[154:157], v[170:173], v[114:117]
	v_mfma_f32_16x16x32_bf16 v[102:105], v[146:149], v[178:181], v[102:105]
	v_mfma_f32_16x16x32_bf16 v[98:101], v[154:157], v[178:181], v[98:101]
	v_mfma_f32_16x16x32_bf16 v[82:85], v[146:149], v[216:219], v[82:85]
	v_mfma_f32_16x16x32_bf16 v[74:77], v[154:157], v[216:219], v[74:77]
	v_mfma_f32_16x16x32_bf16 v[134:137], v[150:153], v[166:169], v[134:137]
	v_mfma_f32_16x16x32_bf16 v[130:133], v[158:161], v[166:169], v[130:133]
	v_mfma_f32_16x16x32_bf16 v[118:121], v[150:153], v[174:177], v[118:121]
	v_mfma_f32_16x16x32_bf16 v[114:117], v[158:161], v[174:177], v[114:117]
	v_mfma_f32_16x16x32_bf16 v[102:105], v[150:153], v[182:185], v[102:105]
	v_mfma_f32_16x16x32_bf16 v[98:101], v[158:161], v[182:185], v[98:101]
	v_mfma_f32_16x16x32_bf16 v[82:85], v[150:153], v[220:223], v[82:85]
	v_mfma_f32_16x16x32_bf16 v[74:77], v[158:161], v[220:223], v[74:77]
	s_setprio 1
	s_barrier
; #define PG8_STAGE(bufoff, gbase, voff) do { _Pragma("unroll") for (int _i = 0; _i < 2; ++_i) \
;         __builtin_amdgcn_global_load_lds((const unsigned*)((const char*)(gbase) + (voff)[_i]), (PG8_LAS unsigned*)(lds + (bufoff) + ldsw + _i * 8192), 16, 0, 0); } while (0)
; #define PG8_LDA(dst, b, h) do { _Pragma("unroll") for (int m = 0; m < 4; ++m) _Pragma("unroll") for (int k = 0; k < 2; ++k) dst[m][k] = *(const PG8_LAS bf16x8*)(lds + PG8_SA(b, h) + aoff + m * 2048 + k * 1024); } while (0)
; #define PG8_MMA(ai, bj, At, Bt) do { __builtin_amdgcn_s_setprio(1); _Pragma("unroll") for (int m = 0; m < 4; ++m) _Pragma("unroll") for (int n = 0; n < 2; ++n) _Pragma("unroll") for (int k = 0; k < 2; ++k) \
;         acc[ai][bj][m][n] = __builtin_amdgcn_mfma_f32_16x16x32_bf16(Bt[n][k], At[m][k], acc[ai][bj][m][n], 0, 0, 0); __builtin_amdgcn_s_setprio(0); } while (0)
; #define PG8_WAIT_V(n) asm volatile("s_waitcnt vmcnt(" #n ")" ::: "memory")
; #define PG8_WAIT_L(n) asm volatile("s_waitcnt lgkmcnt(" #n ")" ::: "memory")
; #define PG8_BAR __builtin_amdgcn_s_barrier()
; #define PG8_SCHED __builtin_amdgcn_sched_barrier(0)
; template <class Epi, class Sched, bool ALIGN_EPI = false, bool SP2 = false>
; __device__ __forceinline__ void gemm_phase(PG8_LAS unsigned char* lds, const Gemm g, const Sched& S, const Epi& E) {
;     ...
;             PG8_LDA(At, 1, 1); PG8_STAGE(PG8_SB(1, 0), b3, voffB); PG8_STAGE(PG8_SB(1, 1), b3 + hstepB, voffB); PG8_STAGE(PG8_SA(1, 0), a3, voffA);
;             PG8_WAIT_V(8); PG8_WAIT_L(0); PG8_BAR; PG8_MMA(1, 0, At, B0); PG8_MMA(1, 1, At, B1); PG8_BAR; PG8_SCHED;
	s_add_i32 s9, s9, s25
	v_lshl_add_u64 v[194:195], v[194:195], 0, s[60:61]
	s_mov_b32 m0, s9
	ds_read_b128 v[162:165], v236 offset:49152
	ds_read_b128 v[166:169], v236 offset:50176
	ds_read_b128 v[170:173], v236 offset:51200
	ds_read_b128 v[174:177], v236 offset:52224
	ds_read_b128 v[178:181], v236 offset:53248
	ds_read_b128 v[182:185], v236 offset:54272
	ds_read_b128 v[216:219], v236 offset:55296
	ds_read_b128 v[220:223], v236 offset:56320
	global_load_lds_dwordx4 v[194:195], off
	s_add_i32 m0, s9, 0x2000
	s_add_u32 s10, s46, 0x20080
	v_lshl_add_u64 v[194:195], v[196:197], 0, s[60:61]
	s_addc_u32 s11, s47, 0
	s_add_i32 s9, s12, s25
	global_load_lds_dwordx4 v[194:195], off
	v_lshl_add_u64 v[194:195], s[10:11], 0, v[190:191]
	s_mov_b32 m0, s9
	s_nop 0
	global_load_lds_dwordx4 v[194:195], off
	v_lshl_add_u64 v[194:195], s[10:11], 0, v[206:207]
	s_add_i32 m0, s9, 0x2000
	s_nop 0
	global_load_lds_dwordx4 v[194:195], off
	v_lshl_add_u64 v[194:195], v[198:199], 0, s[60:61]
	s_mov_b32 m0, s75
	s_nop 0
	global_load_lds_dwordx4 v[194:195], off
	v_lshl_add_u64 v[194:195], v[238:239], 0, s[60:61]
	s_mov_b32 m0, s0
	s_nop 0
	global_load_lds_dwordx4 v[194:195], off
	s_waitcnt vmcnt(8)
	s_waitcnt lgkmcnt(0)
	s_barrier
	s_setprio 0
	s_waitcnt lgkmcnt(0)
	v_mfma_f32_16x16x32_bf16 v[62:65], v[66:69], v[162:165], v[62:65]
	v_mfma_f32_16x16x32_bf16 v[58:61], v[78:81], v[162:165], v[58:61]
	v_mfma_f32_16x16x32_bf16 v[46:49], v[66:69], v[170:173], v[46:49]
	v_mfma_f32_16x16x32_bf16 v[42:45], v[78:81], v[170:173], v[42:45]
	v_mfma_f32_16x16x32_bf16 v[30:33], v[66:69], v[178:181], v[30:33]
	v_mfma_f32_16x16x32_bf16 v[26:29], v[78:81], v[178:181], v[26:29]
	v_mfma_f32_16x16x32_bf16 v[14:17], v[66:69], v[216:219], v[14:17]
	v_mfma_f32_16x16x32_bf16 v[10:13], v[78:81], v[216:219], v[10:13]
	v_mfma_f32_16x16x32_bf16 v[62:65], v[70:73], v[166:169], v[62:65]
	v_mfma_f32_16x16x32_bf16 v[58:61], v[86:89], v[166:169], v[58:61]
	v_mfma_f32_16x16x32_bf16 v[46:49], v[70:73], v[174:177], v[46:49]
	v_mfma_f32_16x16x32_bf16 v[42:45], v[86:89], v[174:177], v[42:45]
	v_mfma_f32_16x16x32_bf16 v[30:33], v[70:73], v[182:185], v[30:33]
	v_mfma_f32_16x16x32_bf16 v[26:29], v[86:89], v[182:185], v[26:29]
	v_mfma_f32_16x16x32_bf16 v[14:17], v[70:73], v[220:223], v[14:17]
	v_mfma_f32_16x16x32_bf16 v[10:13], v[86:89], v[220:223], v[10:13]
	v_mfma_f32_16x16x32_bf16 v[54:57], v[146:149], v[162:165], v[54:57]
	v_mfma_f32_16x16x32_bf16 v[50:53], v[154:157], v[162:165], v[50:53]
	v_mfma_f32_16x16x32_bf16 v[38:41], v[146:149], v[170:173], v[38:41]
	v_mfma_f32_16x16x32_bf16 v[34:37], v[154:157], v[170:173], v[34:37]
	v_mfma_f32_16x16x32_bf16 v[22:25], v[146:149], v[178:181], v[22:25]
	v_mfma_f32_16x16x32_bf16 v[18:21], v[154:157], v[178:181], v[18:21]
	v_mfma_f32_16x16x32_bf16 v[6:9], v[146:149], v[216:219], v[6:9]
	v_mfma_f32_16x16x32_bf16 v[2:5], v[154:157], v[216:219], v[2:5]
	v_mfma_f32_16x16x32_bf16 v[54:57], v[150:153], v[166:169], v[54:57]
	v_mfma_f32_16x16x32_bf16 v[50:53], v[158:161], v[166:169], v[50:53]
	v_mfma_f32_16x16x32_bf16 v[38:41], v[150:153], v[174:177], v[38:41]
	v_mfma_f32_16x16x32_bf16 v[34:37], v[158:161], v[174:177], v[34:37]
	v_mfma_f32_16x16x32_bf16 v[22:25], v[150:153], v[182:185], v[22:25]
	v_mfma_f32_16x16x32_bf16 v[18:21], v[158:161], v[182:185], v[18:21]
	v_mfma_f32_16x16x32_bf16 v[6:9], v[150:153], v[220:223], v[6:9]
	v_mfma_f32_16x16x32_bf16 v[2:5], v[158:161], v[220:223], v[2:5]
	s_setprio 1
	s_barrier
	s_add_i32 s8, s8, 2
	s_add_u32 s38, s38, 0x100
	s_addc_u32 s39, s39, 0
	s_add_u32 s6, s6, 0x100
	s_addc_u32 s7, s7, 0
	s_cmp_gt_u32 s8, 29
	s_cbranch_scc0 .LBB0_927
	s_setprio 0
	s_and_b64 vcc, exec, s[70:71]
	s_cbranch_vccz .LBB0_930
	s_barrier

; #define PG8_STAGE(bufoff, gbase, voff) do { _Pragma("unroll") for (int _i = 0; _i < 2; ++_i) \
;         __builtin_amdgcn_global_load_lds((const unsigned*)((const char*)(gbase) + (voff)[_i]), (PG8_LAS unsigned*)(lds + (bufoff) + ldsw + _i * 8192), 16, 0, 0); } while (0)
; #define PG8_LDA(dst, b, h) do { _Pragma("unroll") for (int m = 0; m < 4; ++m) _Pragma("unroll") for (int k = 0; k < 2; ++k) dst[m][k] = *(const PG8_LAS bf16x8*)(lds + PG8_SA(b, h) + aoff + m * 2048 + k * 1024); } while (0)
; #define PG8_LDB(dst, b, h) do { _Pragma("unroll") for (int n = 0; n < 2; ++n) _Pragma("unroll") for (int k = 0; k < 2; ++k) dst[n][k] = *(const PG8_LAS bf16x8*)(lds + PG8_SB(b, h) + boff + n * 2048 + k * 1024); } while (0)
; #define PG8_MMA(ai, bj, At, Bt) do { __builtin_amdgcn_s_setprio(1); _Pragma("unroll") for (int m = 0; m < 4; ++m) _Pragma("unroll") for (int n = 0; n < 2; ++n) _Pragma("unroll") for (int k = 0; k < 2; ++k) \
;         acc[ai][bj][m][n] = __builtin_amdgcn_mfma_f32_16x16x32_bf16(Bt[n][k], At[m][k], acc[ai][bj][m][n], 0, 0, 0); __builtin_amdgcn_s_setprio(0); } while (0)
; #define PG8_WAIT_V(n) asm volatile("s_waitcnt vmcnt(" #n ")" ::: "memory")
; #define PG8_WAIT_L(n) asm volatile("s_waitcnt lgkmcnt(" #n ")" ::: "memory")
; template <class Epi, class Sched, bool ALIGN_EPI = false, bool SP2 = false>
; __device__ __forceinline__ void gemm_phase(PG8_LAS unsigned char* lds, const Gemm g, const Sched& S, const Epi& E) {
;     ...
;             const bool last = (t == nt - 2);
;             const char* a1 = cA + (size_t)(t + 1) * kstep;
;             const char* a2 = last ? nA : cA + (size_t)(t + 2) * kstep; const char* b2 = last ? nB : cB + (size_t)(t + 2) * kstep;
;             const char* a3 = a2 + kstep; const char* b3 = b2 + kstep;
;             if (last && has_next) S.a_ready(nxt);
;             if constexpr (SP2) {
;             PG8_LDB(B0, 0, 0); PG8_LDB(B1, 0, 1); PG8_SCHED; PG8_LDA(At, 0, 0); PG8_STAGE(PG8_SA(1, 1), a1 + hstep, voffA);
;             PG8_WAIT_V(8); PG8_WAIT_L(0); PG8_BAR; PG8_MMA(0, 0, At, B0); PG8_MMA(0, 1, At, B1); PG8_BAR; PG8_SCHED;
;             PG8_LDA(At, 0, 1); PG8_STAGE(PG8_SB(0, 0), b2, voffB); PG8_STAGE(PG8_SB(0, 1), b2 + hstepB, voffB); PG8_STAGE(PG8_SA(0, 0), a2, voffA);
;             PG8_WAIT_V(8); PG8_WAIT_L(0); PG8_BAR; PG8_MMA(1, 0, At, B0); PG8_MMA(1, 1, At, B1); PG8_BAR; PG8_SCHED;
.LBB0_1071:
	s_add_u32 s10, s38, 0xffe00080
	s_addc_u32 s11, s39, -1
	s_add_i32 s12, 0, 0x10000
	s_cmpk_eq_i32 s9, 0x7c
	s_cselect_b32 vcc_hi, s97, s11
	s_cselect_b32 vcc_lo, s4, s10
	s_cselect_b32 s47, s5, s8
	s_cselect_b32 s46, s6, s7
	s_add_i32 s13, 0, 0x14000
	v_add_u32_e32 v152, s12, v164
	v_add_u32_e32 v167, s13, v164
	ds_read_b128 v[130:133], v152
	ds_read_b128 v[134:137], v152 offset:1024
	ds_read_b128 v[138:141], v152 offset:2048
	ds_read_b128 v[152:155], v152 offset:3072
	ds_read_b128 v[156:159], v167
	ds_read_b128 v[160:163], v167 offset:1024
	ds_read_b128 v[168:171], v167 offset:2048
	ds_read_b128 v[172:175], v167 offset:3072
	v_lshl_add_u64 v[184:185], s[38:39], 0, v[148:149]
	s_add_i32 m0, s74, 0xc000
	ds_read_b128 v[176:179], v166
	ds_read_b128 v[180:183], v166 offset:1024
	ds_read_b128 v[206:209], v166 offset:2048
	ds_read_b128 v[210:213], v166 offset:3072
	ds_read_b128 v[214:217], v166 offset:4096
	ds_read_b128 v[218:221], v166 offset:5120
	ds_read_b128 v[236:239], v166 offset:6144
	ds_read_b128 v[240:243], v166 offset:7168
	global_load_lds_dwordx4 v[184:185], off
	v_lshl_add_u64 v[184:185], s[38:39], 0, v[150:151]
	s_add_i32 m0, s74, 0xe000
	s_nop 0
	global_load_lds_dwordx4 v[184:185], off
	s_waitcnt vmcnt(8)
	s_waitcnt lgkmcnt(0)
	s_barrier
	s_setprio 0
	s_waitcnt lgkmcnt(0)
	v_mfma_f32_16x16x32_bf16 v[126:129], v[130:133], v[176:179], v[126:129]
	v_mfma_f32_16x16x32_bf16 v[122:125], v[138:141], v[176:179], v[122:125]
	v_mfma_f32_16x16x32_bf16 v[110:113], v[130:133], v[206:209], v[110:113]
	v_mfma_f32_16x16x32_bf16 v[106:109], v[138:141], v[206:209], v[106:109]
	v_mfma_f32_16x16x32_bf16 v[94:97], v[130:133], v[214:217], v[94:97]
	v_mfma_f32_16x16x32_bf16 v[90:93], v[138:141], v[214:217], v[90:93]
	v_mfma_f32_16x16x32_bf16 v[78:81], v[130:133], v[236:239], v[78:81]
	v_mfma_f32_16x16x32_bf16 v[74:77], v[138:141], v[236:239], v[74:77]
	v_mfma_f32_16x16x32_bf16 v[126:129], v[134:137], v[180:183], v[126:129]
	v_mfma_f32_16x16x32_bf16 v[122:125], v[152:155], v[180:183], v[122:125]
	v_mfma_f32_16x16x32_bf16 v[110:113], v[134:137], v[210:213], v[110:113]
	v_mfma_f32_16x16x32_bf16 v[106:109], v[152:155], v[210:213], v[106:109]
	v_mfma_f32_16x16x32_bf16 v[94:97], v[134:137], v[218:221], v[94:97]
	v_mfma_f32_16x16x32_bf16 v[90:93], v[152:155], v[218:221], v[90:93]
	v_mfma_f32_16x16x32_bf16 v[78:81], v[134:137], v[240:243], v[78:81]
	v_mfma_f32_16x16x32_bf16 v[74:77], v[152:155], v[240:243], v[74:77]
	v_mfma_f32_16x16x32_bf16 v[118:121], v[156:159], v[176:179], v[118:121]
	v_mfma_f32_16x16x32_bf16 v[114:117], v[168:171], v[176:179], v[114:117]
	v_mfma_f32_16x16x32_bf16 v[102:105], v[156:159], v[206:209], v[102:105]
	v_mfma_f32_16x16x32_bf16 v[98:101], v[168:171], v[206:209], v[98:101]
	v_mfma_f32_16x16x32_bf16 v[86:89], v[156:159], v[214:217], v[86:89]
	v_mfma_f32_16x16x32_bf16 v[82:85], v[168:171], v[214:217], v[82:85]
	v_mfma_f32_16x16x32_bf16 v[70:73], v[156:159], v[236:239], v[70:73]
	v_mfma_f32_16x16x32_bf16 v[66:69], v[168:171], v[236:239], v[66:69]
	v_mfma_f32_16x16x32_bf16 v[118:121], v[160:163], v[180:183], v[118:121]
	v_mfma_f32_16x16x32_bf16 v[114:117], v[172:175], v[180:183], v[114:117]
	v_mfma_f32_16x16x32_bf16 v[102:105], v[160:163], v[210:213], v[102:105]
	v_mfma_f32_16x16x32_bf16 v[98:101], v[172:175], v[210:213], v[98:101]
	v_mfma_f32_16x16x32_bf16 v[86:89], v[160:163], v[218:221], v[86:89]
	v_mfma_f32_16x16x32_bf16 v[82:85], v[172:175], v[218:221], v[82:85]
	v_mfma_f32_16x16x32_bf16 v[70:73], v[160:163], v[240:243], v[70:73]
	v_mfma_f32_16x16x32_bf16 v[66:69], v[172:175], v[240:243], v[66:69]
	s_setprio 1
	s_barrier
	s_add_i32 s10, s12, s67
	v_lshl_add_u64 v[184:185], s[46:47], 0, v[146:147]
	s_mov_b32 m0, s10
	ds_read_b128 v[176:179], v166 offset:16384
	ds_read_b128 v[180:183], v166 offset:17408
	ds_read_b128 v[206:209], v166 offset:18432
	ds_read_b128 v[210:213], v166 offset:19456
	ds_read_b128 v[214:217], v166 offset:20480
	ds_read_b128 v[218:221], v166 offset:21504
	ds_read_b128 v[236:239], v166 offset:22528
	ds_read_b128 v[240:243], v166 offset:23552
	global_load_lds_dwordx4 v[184:185], off
	s_add_i32 m0, s10, 0x2000
	s_add_u32 s10, s46, 0x80000
	v_lshl_add_u64 v[194:195], s[46:47], 0, v[142:143]
	s_addc_u32 s11, s47, 0
	s_add_i32 s12, s13, s67
	global_load_lds_dwordx4 v[194:195], off
	v_lshl_add_u64 v[196:197], s[10:11], 0, v[146:147]
	s_mov_b32 m0, s12
	v_lshl_add_u64 v[198:199], vcc, 0, v[144:145]
	global_load_lds_dwordx4 v[196:197], off
	v_lshl_add_u64 v[196:197], s[10:11], 0, v[142:143]
	s_add_i32 m0, s12, 0x2000
	s_nop 0
	global_load_lds_dwordx4 v[196:197], off
	v_lshl_add_u64 v[196:197], vcc, 0, v[190:191]
	s_mov_b32 m0, s74
	s_nop 0
	global_load_lds_dwordx4 v[196:197], off
	s_mov_b32 m0, s75
	s_nop 0
	global_load_lds_dwordx4 v[198:199], off
	s_waitcnt vmcnt(8)
	s_waitcnt lgkmcnt(0)
	s_barrier
; #define PG8_STAGE(bufoff, gbase, voff) do { _Pragma("unroll") for (int _i = 0; _i < 2; ++_i) \
;         __builtin_amdgcn_global_load_lds((const unsigned*)((const char*)(gbase) + (voff)[_i]), (PG8_LAS unsigned*)(lds + (bufoff) + ldsw + _i * 8192), 16, 0, 0); } while (0)
; #define PG8_LDA(dst, b, h) do { _Pragma("unroll") for (int m = 0; m < 4; ++m) _Pragma("unroll") for (int k = 0; k < 2; ++k) dst[m][k] = *(const PG8_LAS bf16x8*)(lds + PG8_SA(b, h) + aoff + m * 2048 + k * 1024); } while (0)
; #define PG8_LDB(dst, b, h) do { _Pragma("unroll") for (int n = 0; n < 2; ++n) _Pragma("unroll") for (int k = 0; k < 2; ++k) dst[n][k] = *(const PG8_LAS bf16x8*)(lds + PG8_SB(b, h) + boff + n * 2048 + k * 1024); } while (0)
; #define PG8_MMA(ai, bj, At, Bt) do { __builtin_amdgcn_s_setprio(1); _Pragma("unroll") for (int m = 0; m < 4; ++m) _Pragma("unroll") for (int n = 0; n < 2; ++n) _Pragma("unroll") for (int k = 0; k < 2; ++k) \
;         acc[ai][bj][m][n] = __builtin_amdgcn_mfma_f32_16x16x32_bf16(Bt[n][k], At[m][k], acc[ai][bj][m][n], 0, 0, 0); __builtin_amdgcn_s_setprio(0); } while (0)
; #define PG8_WAIT_V(n) asm volatile("s_waitcnt vmcnt(" #n ")" ::: "memory")
; #define PG8_WAIT_L(n) asm volatile("s_waitcnt lgkmcnt(" #n ")" ::: "memory")
; #define PG8_BAR __builtin_amdgcn_s_barrier()
; #define PG8_SCHED __builtin_amdgcn_sched_barrier(0)
; template <class Epi, class Sched, bool ALIGN_EPI = false, bool SP2 = false>
; __device__ __forceinline__ void gemm_phase(PG8_LAS unsigned char* lds, const Gemm g, const Sched& S, const Epi& E) {
;     ...
;             PG8_WAIT_V(8); PG8_WAIT_L(0); PG8_BAR; PG8_MMA(1, 0, At, B0); PG8_MMA(1, 1, At, B1); PG8_BAR; PG8_SCHED;
;             PG8_LDB(B0, 1, 0); PG8_LDB(B1, 1, 1); PG8_SCHED; PG8_LDA(At, 1, 0); PG8_STAGE(PG8_SA(0, 1), a2 + hstep, voffA);
;             PG8_WAIT_V(8); PG8_WAIT_L(0); PG8_BAR; PG8_MMA(0, 0, At, B0); PG8_MMA(0, 1, At, B1); PG8_BAR; PG8_SCHED;
	s_setprio 0
	s_waitcnt lgkmcnt(0)
	v_mfma_f32_16x16x32_bf16 v[62:65], v[130:133], v[176:179], v[62:65]
	v_mfma_f32_16x16x32_bf16 v[58:61], v[138:141], v[176:179], v[58:61]
	v_mfma_f32_16x16x32_bf16 v[46:49], v[130:133], v[206:209], v[46:49]
	v_mfma_f32_16x16x32_bf16 v[42:45], v[138:141], v[206:209], v[42:45]
	v_mfma_f32_16x16x32_bf16 v[30:33], v[130:133], v[214:217], v[30:33]
	v_mfma_f32_16x16x32_bf16 v[26:29], v[138:141], v[214:217], v[26:29]
	v_mfma_f32_16x16x32_bf16 v[14:17], v[130:133], v[236:239], v[14:17]
	v_mfma_f32_16x16x32_bf16 v[10:13], v[138:141], v[236:239], v[10:13]
	v_mfma_f32_16x16x32_bf16 v[62:65], v[134:137], v[180:183], v[62:65]
	v_mfma_f32_16x16x32_bf16 v[58:61], v[152:155], v[180:183], v[58:61]
	v_mfma_f32_16x16x32_bf16 v[46:49], v[134:137], v[210:213], v[46:49]
	v_mfma_f32_16x16x32_bf16 v[42:45], v[152:155], v[210:213], v[42:45]
	v_mfma_f32_16x16x32_bf16 v[30:33], v[134:137], v[218:221], v[30:33]
	v_mfma_f32_16x16x32_bf16 v[26:29], v[152:155], v[218:221], v[26:29]
	v_mfma_f32_16x16x32_bf16 v[14:17], v[134:137], v[240:243], v[14:17]
	v_mfma_f32_16x16x32_bf16 v[10:13], v[152:155], v[240:243], v[10:13]
	v_mfma_f32_16x16x32_bf16 v[54:57], v[156:159], v[176:179], v[54:57]
	v_mfma_f32_16x16x32_bf16 v[50:53], v[168:171], v[176:179], v[50:53]
	v_mfma_f32_16x16x32_bf16 v[38:41], v[156:159], v[206:209], v[38:41]
	v_mfma_f32_16x16x32_bf16 v[34:37], v[168:171], v[206:209], v[34:37]
	v_mfma_f32_16x16x32_bf16 v[22:25], v[156:159], v[214:217], v[22:25]
	v_mfma_f32_16x16x32_bf16 v[18:21], v[168:171], v[214:217], v[18:21]
	v_mfma_f32_16x16x32_bf16 v[6:9], v[156:159], v[236:239], v[6:9]
	v_mfma_f32_16x16x32_bf16 v[2:5], v[168:171], v[236:239], v[2:5]
	v_mfma_f32_16x16x32_bf16 v[54:57], v[160:163], v[180:183], v[54:57]
	v_mfma_f32_16x16x32_bf16 v[50:53], v[172:175], v[180:183], v[50:53]
	v_mfma_f32_16x16x32_bf16 v[38:41], v[160:163], v[210:213], v[38:41]
	v_mfma_f32_16x16x32_bf16 v[34:37], v[172:175], v[210:213], v[34:37]
	v_mfma_f32_16x16x32_bf16 v[22:25], v[160:163], v[218:221], v[22:25]
	v_mfma_f32_16x16x32_bf16 v[18:21], v[172:175], v[218:221], v[18:21]
	v_mfma_f32_16x16x32_bf16 v[6:9], v[160:163], v[240:243], v[6:9]
	v_mfma_f32_16x16x32_bf16 v[2:5], v[172:175], v[240:243], v[2:5]
	s_setprio 1
	s_barrier
	s_add_i32 s12, 0, 0x18000
	s_add_i32 s13, 0, 0x1c000
	v_add_u32_e32 v152, s12, v164
	v_add_u32_e32 v167, s13, v164
	ds_read_b128 v[130:133], v152
	ds_read_b128 v[134:137], v152 offset:1024
	ds_read_b128 v[138:141], v152 offset:2048
	ds_read_b128 v[152:155], v152 offset:3072
	ds_read_b128 v[156:159], v167
	ds_read_b128 v[160:163], v167 offset:1024
	ds_read_b128 v[168:171], v167 offset:2048
	ds_read_b128 v[172:175], v167 offset:3072
	s_add_u32 s10, vcc_lo, 0x200000
	s_addc_u32 s11, vcc_hi, 0
	s_mov_b32 m0, s86
	v_lshl_add_u64 v[222:223], s[10:11], 0, v[190:191]
	ds_read_b128 v[176:179], v166 offset:32768
	ds_read_b128 v[180:183], v166 offset:33792
	ds_read_b128 v[206:209], v166 offset:34816
	ds_read_b128 v[210:213], v166 offset:35840
	ds_read_b128 v[214:217], v166 offset:36864
	ds_read_b128 v[218:221], v166 offset:37888
	ds_read_b128 v[236:239], v166 offset:38912
	ds_read_b128 v[240:243], v166 offset:39936
	global_load_lds_dwordx4 v[222:223], off
	v_lshl_add_u64 v[222:223], s[10:11], 0, v[144:145]
	s_mov_b32 m0, s87
	s_nop 0
	global_load_lds_dwordx4 v[222:223], off
	s_waitcnt vmcnt(8)
	s_waitcnt lgkmcnt(0)
	s_barrier
	s_setprio 0
	s_waitcnt lgkmcnt(0)
	v_mfma_f32_16x16x32_bf16 v[126:129], v[130:133], v[176:179], v[126:129]
	v_mfma_f32_16x16x32_bf16 v[122:125], v[138:141], v[176:179], v[122:125]
	v_mfma_f32_16x16x32_bf16 v[110:113], v[130:133], v[206:209], v[110:113]
	v_mfma_f32_16x16x32_bf16 v[106:109], v[138:141], v[206:209], v[106:109]
	v_mfma_f32_16x16x32_bf16 v[94:97], v[130:133], v[214:217], v[94:97]
	v_mfma_f32_16x16x32_bf16 v[90:93], v[138:141], v[214:217], v[90:93]
	v_mfma_f32_16x16x32_bf16 v[78:81], v[130:133], v[236:239], v[78:81]
	v_mfma_f32_16x16x32_bf16 v[74:77], v[138:141], v[236:239], v[74:77]
	v_mfma_f32_16x16x32_bf16 v[126:129], v[134:137], v[180:183], v[126:129]
	v_mfma_f32_16x16x32_bf16 v[122:125], v[152:155], v[180:183], v[122:125]
	v_mfma_f32_16x16x32_bf16 v[110:113], v[134:137], v[210:213], v[110:113]
	v_mfma_f32_16x16x32_bf16 v[106:109], v[152:155], v[210:213], v[106:109]
	v_mfma_f32_16x16x32_bf16 v[94:97], v[134:137], v[218:221], v[94:97]
	v_mfma_f32_16x16x32_bf16 v[90:93], v[152:155], v[218:221], v[90:93]
	v_mfma_f32_16x16x32_bf16 v[78:81], v[134:137], v[240:243], v[78:81]
	v_mfma_f32_16x16x32_bf16 v[74:77], v[152:155], v[240:243], v[74:77]
	v_mfma_f32_16x16x32_bf16 v[118:121], v[156:159], v[176:179], v[118:121]
	v_mfma_f32_16x16x32_bf16 v[114:117], v[168:171], v[176:179], v[114:117]
	v_mfma_f32_16x16x32_bf16 v[102:105], v[156:159], v[206:209], v[102:105]
	v_mfma_f32_16x16x32_bf16 v[98:101], v[168:171], v[206:209], v[98:101]
	v_mfma_f32_16x16x32_bf16 v[86:89], v[156:159], v[214:217], v[86:89]
	v_mfma_f32_16x16x32_bf16 v[82:85], v[168:171], v[214:217], v[82:85]
	v_mfma_f32_16x16x32_bf16 v[70:73], v[156:159], v[236:239], v[70:73]
	v_mfma_f32_16x16x32_bf16 v[66:69], v[168:171], v[236:239], v[66:69]
	v_mfma_f32_16x16x32_bf16 v[118:121], v[160:163], v[180:183], v[118:121]
	v_mfma_f32_16x16x32_bf16 v[114:117], v[172:175], v[180:183], v[114:117]
	v_mfma_f32_16x16x32_bf16 v[102:105], v[160:163], v[210:213], v[102:105]
	v_mfma_f32_16x16x32_bf16 v[98:101], v[172:175], v[210:213], v[98:101]
	v_mfma_f32_16x16x32_bf16 v[86:89], v[160:163], v[218:221], v[86:89]
	v_mfma_f32_16x16x32_bf16 v[82:85], v[172:175], v[218:221], v[82:85]
	v_mfma_f32_16x16x32_bf16 v[70:73], v[160:163], v[240:243], v[70:73]
	v_mfma_f32_16x16x32_bf16 v[66:69], v[172:175], v[240:243], v[66:69]
	s_setprio 1
	s_barrier
; #define PG8_STAGE(bufoff, gbase, voff) do { _Pragma("unroll") for (int _i = 0; _i < 2; ++_i) \
;         __builtin_amdgcn_global_load_lds((const unsigned*)((const char*)(gbase) + (voff)[_i]), (PG8_LAS unsigned*)(lds + (bufoff) + ldsw + _i * 8192), 16, 0, 0); } while (0)
; #define PG8_LDA(dst, b, h) do { _Pragma("unroll") for (int m = 0; m < 4; ++m) _Pragma("unroll") for (int k = 0; k < 2; ++k) dst[m][k] = *(const PG8_LAS bf16x8*)(lds + PG8_SA(b, h) + aoff + m * 2048 + k * 1024); } while (0)
; #define PG8_MMA(ai, bj, At, Bt) do { __builtin_amdgcn_s_setprio(1); _Pragma("unroll") for (int m = 0; m < 4; ++m) _Pragma("unroll") for (int n = 0; n < 2; ++n) _Pragma("unroll") for (int k = 0; k < 2; ++k) \
;         acc[ai][bj][m][n] = __builtin_amdgcn_mfma_f32_16x16x32_bf16(Bt[n][k], At[m][k], acc[ai][bj][m][n], 0, 0, 0); __builtin_amdgcn_s_setprio(0); } while (0)
; #define PG8_WAIT_V(n) asm volatile("s_waitcnt vmcnt(" #n ")" ::: "memory")
; #define PG8_WAIT_L(n) asm volatile("s_waitcnt lgkmcnt(" #n ")" ::: "memory")
; #define PG8_BAR __builtin_amdgcn_s_barrier()
; #define PG8_SCHED __builtin_amdgcn_sched_barrier(0)
; template <class Epi, class Sched, bool ALIGN_EPI = false, bool SP2 = false>
; __device__ __forceinline__ void gemm_phase(PG8_LAS unsigned char* lds, const Gemm g, const Sched& S, const Epi& E) {
;     ...
;             PG8_LDA(At, 1, 1); PG8_STAGE(PG8_SB(1, 0), b3, voffB); PG8_STAGE(PG8_SB(1, 1), b3 + hstepB, voffB); PG8_STAGE(PG8_SA(1, 0), a3, voffA);
;             PG8_WAIT_V(8); PG8_WAIT_L(0); PG8_BAR; PG8_MMA(1, 0, At, B0); PG8_MMA(1, 1, At, B1); PG8_BAR; PG8_SCHED;
	s_add_i32 s10, s12, s67
	v_lshl_add_u64 v[184:185], v[184:185], 0, s[60:61]
	s_mov_b32 m0, s10
	ds_read_b128 v[176:179], v166 offset:49152
	ds_read_b128 v[180:183], v166 offset:50176
	ds_read_b128 v[206:209], v166 offset:51200
	ds_read_b128 v[210:213], v166 offset:52224
	ds_read_b128 v[214:217], v166 offset:53248
	ds_read_b128 v[218:221], v166 offset:54272
	ds_read_b128 v[236:239], v166 offset:55296
	ds_read_b128 v[240:243], v166 offset:56320
	global_load_lds_dwordx4 v[184:185], off
	s_add_i32 m0, s10, 0x2000
	s_add_u32 s10, s46, 0x80080
	v_lshl_add_u64 v[184:185], v[194:195], 0, s[60:61]
	s_addc_u32 s11, s47, 0
	s_add_i32 s12, s13, s67
	global_load_lds_dwordx4 v[184:185], off
	v_lshl_add_u64 v[184:185], s[10:11], 0, v[146:147]
	s_mov_b32 m0, s12
	s_nop 0
	global_load_lds_dwordx4 v[184:185], off
	v_lshl_add_u64 v[184:185], s[10:11], 0, v[142:143]
	s_add_i32 m0, s12, 0x2000
	s_nop 0
	global_load_lds_dwordx4 v[184:185], off
	v_lshl_add_u64 v[184:185], v[196:197], 0, s[60:61]
	s_mov_b32 m0, s82
	s_nop 0
	global_load_lds_dwordx4 v[184:185], off
	v_lshl_add_u64 v[184:185], v[198:199], 0, s[60:61]
	s_mov_b32 m0, s42
	s_nop 0
	global_load_lds_dwordx4 v[184:185], off
	s_waitcnt vmcnt(8)
	s_waitcnt lgkmcnt(0)
	s_barrier
	s_setprio 0
	s_waitcnt lgkmcnt(0)
	v_mfma_f32_16x16x32_bf16 v[62:65], v[130:133], v[176:179], v[62:65]
	v_mfma_f32_16x16x32_bf16 v[58:61], v[138:141], v[176:179], v[58:61]
	v_mfma_f32_16x16x32_bf16 v[46:49], v[130:133], v[206:209], v[46:49]
	v_mfma_f32_16x16x32_bf16 v[42:45], v[138:141], v[206:209], v[42:45]
	v_mfma_f32_16x16x32_bf16 v[30:33], v[130:133], v[214:217], v[30:33]
	v_mfma_f32_16x16x32_bf16 v[26:29], v[138:141], v[214:217], v[26:29]
	v_mfma_f32_16x16x32_bf16 v[14:17], v[130:133], v[236:239], v[14:17]
	v_mfma_f32_16x16x32_bf16 v[10:13], v[138:141], v[236:239], v[10:13]
	v_mfma_f32_16x16x32_bf16 v[62:65], v[134:137], v[180:183], v[62:65]
	v_mfma_f32_16x16x32_bf16 v[58:61], v[152:155], v[180:183], v[58:61]
	v_mfma_f32_16x16x32_bf16 v[46:49], v[134:137], v[210:213], v[46:49]
	v_mfma_f32_16x16x32_bf16 v[42:45], v[152:155], v[210:213], v[42:45]
	v_mfma_f32_16x16x32_bf16 v[30:33], v[134:137], v[218:221], v[30:33]
	v_mfma_f32_16x16x32_bf16 v[26:29], v[152:155], v[218:221], v[26:29]
	v_mfma_f32_16x16x32_bf16 v[14:17], v[134:137], v[240:243], v[14:17]
	v_mfma_f32_16x16x32_bf16 v[10:13], v[152:155], v[240:243], v[10:13]
	v_mfma_f32_16x16x32_bf16 v[54:57], v[156:159], v[176:179], v[54:57]
	v_mfma_f32_16x16x32_bf16 v[50:53], v[168:171], v[176:179], v[50:53]
	v_mfma_f32_16x16x32_bf16 v[38:41], v[156:159], v[206:209], v[38:41]
	v_mfma_f32_16x16x32_bf16 v[34:37], v[168:171], v[206:209], v[34:37]
	v_mfma_f32_16x16x32_bf16 v[22:25], v[156:159], v[214:217], v[22:25]
	v_mfma_f32_16x16x32_bf16 v[18:21], v[168:171], v[214:217], v[18:21]
	v_mfma_f32_16x16x32_bf16 v[6:9], v[156:159], v[236:239], v[6:9]
	v_mfma_f32_16x16x32_bf16 v[2:5], v[168:171], v[236:239], v[2:5]
	v_mfma_f32_16x16x32_bf16 v[54:57], v[160:163], v[180:183], v[54:57]
	v_mfma_f32_16x16x32_bf16 v[50:53], v[172:175], v[180:183], v[50:53]
	v_mfma_f32_16x16x32_bf16 v[38:41], v[160:163], v[210:213], v[38:41]
	v_mfma_f32_16x16x32_bf16 v[34:37], v[172:175], v[210:213], v[34:37]
	v_mfma_f32_16x16x32_bf16 v[22:25], v[160:163], v[218:221], v[22:25]
	v_mfma_f32_16x16x32_bf16 v[18:21], v[172:175], v[218:221], v[18:21]
	v_mfma_f32_16x16x32_bf16 v[6:9], v[160:163], v[240:243], v[6:9]
	v_mfma_f32_16x16x32_bf16 v[2:5], v[172:175], v[240:243], v[2:5]
	s_setprio 1
	s_barrier
	s_add_i32 s9, s9, 2
	s_add_u32 s38, s38, 0x100
	s_addc_u32 s39, s39, 0
	s_add_u32 s7, s7, 0x100
	s_addc_u32 s8, s8, 0
	s_cmpk_gt_u32 s9, 0x7d
	s_cbranch_scc0 .LBB0_1071
	s_setprio 0
	s_and_b64 vcc, exec, s[72:73]
	s_cbranch_vccz .LBB0_1074
	s_barrier

; #define PG8_STAGE(bufoff, gbase, voff) do { _Pragma("unroll") for (int _i = 0; _i < 2; ++_i) \
;         __builtin_amdgcn_global_load_lds((const unsigned*)((const char*)(gbase) + (voff)[_i]), (PG8_LAS unsigned*)(lds + (bufoff) + ldsw + _i * 8192), 16, 0, 0); } while (0)
; #define PG8_LDA(dst, b, h) do { _Pragma("unroll") for (int m = 0; m < 4; ++m) _Pragma("unroll") for (int k = 0; k < 2; ++k) dst[m][k] = *(const PG8_LAS bf16x8*)(lds + PG8_SA(b, h) + aoff + m * 2048 + k * 1024); } while (0)
; #define PG8_LDB(dst, b, h) do { _Pragma("unroll") for (int n = 0; n < 2; ++n) _Pragma("unroll") for (int k = 0; k < 2; ++k) dst[n][k] = *(const PG8_LAS bf16x8*)(lds + PG8_SB(b, h) + boff + n * 2048 + k * 1024); } while (0)
; #define PG8_MMA(ai, bj, At, Bt) do { __builtin_amdgcn_s_setprio(1); _Pragma("unroll") for (int m = 0; m < 4; ++m) _Pragma("unroll") for (int n = 0; n < 2; ++n) _Pragma("unroll") for (int k = 0; k < 2; ++k) \
;         acc[ai][bj][m][n] = __builtin_amdgcn_mfma_f32_16x16x32_bf16(Bt[n][k], At[m][k], acc[ai][bj][m][n], 0, 0, 0); __builtin_amdgcn_s_setprio(0); } while (0)
; #define PG8_WAIT_V(n) asm volatile("s_waitcnt vmcnt(" #n ")" ::: "memory")
; #define PG8_WAIT_L(n) asm volatile("s_waitcnt lgkmcnt(" #n ")" ::: "memory")
; template <class Epi, class Sched, bool ALIGN_EPI = false, bool SP2 = false>
; __device__ __forceinline__ void gemm_phase(PG8_LAS unsigned char* lds, const Gemm g, const Sched& S, const Epi& E) {
;     ...
;             const bool last = (t == nt - 2);
;             const char* a1 = cA + (size_t)(t + 1) * kstep;
;             const char* a2 = last ? nA : cA + (size_t)(t + 2) * kstep; const char* b2 = last ? nB : cB + (size_t)(t + 2) * kstep;
;             const char* a3 = a2 + kstep; const char* b3 = b2 + kstep;
;             if (last && has_next) S.a_ready(nxt);
;             if constexpr (SP2) {
;             PG8_LDB(B0, 0, 0); PG8_LDB(B1, 0, 1); PG8_SCHED; PG8_LDA(At, 0, 0); PG8_STAGE(PG8_SA(1, 1), a1 + hstep, voffA);
;             PG8_WAIT_V(8); PG8_WAIT_L(0); PG8_BAR; PG8_MMA(0, 0, At, B0); PG8_MMA(0, 1, At, B1); PG8_BAR; PG8_SCHED;
;             PG8_LDA(At, 0, 1); PG8_STAGE(PG8_SB(0, 0), b2, voffB); PG8_STAGE(PG8_SB(0, 1), b2 + hstepB, voffB); PG8_STAGE(PG8_SA(0, 0), a2, voffA);
;             PG8_WAIT_V(8); PG8_WAIT_L(0); PG8_BAR; PG8_MMA(1, 0, At, B0); PG8_MMA(1, 1, At, B1); PG8_BAR; PG8_SCHED;
.LBB0_1233:
	s_add_u32 s9, s68, s80
	s_addc_u32 s10, s69, s81
	s_add_u32 s9, s9, 0x100
	s_addc_u32 s10, s10, 0
	s_add_u32 s11, s36, s80
	s_addc_u32 s12, s37, s81
	s_add_i32 s13, 0, 0x10000
	s_cmpk_eq_i32 s80, 0xf00
	s_cselect_b32 s93, s4, s10
	s_cselect_b32 s92, s5, s9
	v_add_u32_e32 v144, s13, v145
	s_cselect_b32 s85, s6, s12
	s_cselect_b32 s84, s7, s11
	s_add_i32 s9, 0, 0x14000
	ds_read_b128 v[152:155], v144
	ds_read_b128 v[156:159], v144 offset:1024
	ds_read_b128 v[160:163], v144 offset:2048
	ds_read_b128 v[164:167], v144 offset:3072
	v_add_u32_e32 v144, s9, v145
	ds_read_b128 v[168:171], v144
	ds_read_b128 v[172:175], v144 offset:1024
	ds_read_b128 v[176:179], v144 offset:2048
	ds_read_b128 v[180:183], v144 offset:3072
	v_lshl_add_u64 v[184:185], v[140:141], 0, s[80:81]
	s_add_i32 m0, s51, 0xc000
	ds_read_b128 v[206:209], v151
	ds_read_b128 v[210:213], v151 offset:1024
	ds_read_b128 v[214:217], v151 offset:2048
	ds_read_b128 v[218:221], v151 offset:3072
	ds_read_b128 v[236:239], v151 offset:4096
	ds_read_b128 v[240:243], v151 offset:5120
	ds_read_b128 v[244:247], v151 offset:6144
	ds_read_b128 v[194:197], v151 offset:7168
	global_load_lds_dwordx4 v[184:185], off
	v_lshl_add_u64 v[184:185], v[142:143], 0, s[80:81]
	s_add_i32 m0, s51, 0xe000
	s_nop 0
	global_load_lds_dwordx4 v[184:185], off
	s_waitcnt vmcnt(8)
	s_waitcnt lgkmcnt(0)
	s_barrier
	s_setprio 0
	s_waitcnt lgkmcnt(0)
	v_mfma_f32_16x16x32_bf16 v[126:129], v[152:155], v[206:209], v[126:129]
	v_mfma_f32_16x16x32_bf16 v[122:125], v[160:163], v[206:209], v[122:125]
	v_mfma_f32_16x16x32_bf16 v[118:121], v[152:155], v[214:217], v[118:121]
	v_mfma_f32_16x16x32_bf16 v[114:117], v[160:163], v[214:217], v[114:117]
	v_mfma_f32_16x16x32_bf16 v[110:113], v[152:155], v[236:239], v[110:113]
	v_mfma_f32_16x16x32_bf16 v[106:109], v[160:163], v[236:239], v[106:109]
	v_mfma_f32_16x16x32_bf16 v[102:105], v[152:155], v[244:247], v[102:105]
	v_mfma_f32_16x16x32_bf16 v[98:101], v[160:163], v[244:247], v[98:101]
	v_mfma_f32_16x16x32_bf16 v[126:129], v[156:159], v[210:213], v[126:129]
	v_mfma_f32_16x16x32_bf16 v[122:125], v[164:167], v[210:213], v[122:125]
	v_mfma_f32_16x16x32_bf16 v[118:121], v[156:159], v[218:221], v[118:121]
	v_mfma_f32_16x16x32_bf16 v[114:117], v[164:167], v[218:221], v[114:117]
	v_mfma_f32_16x16x32_bf16 v[110:113], v[156:159], v[240:243], v[110:113]
	v_mfma_f32_16x16x32_bf16 v[106:109], v[164:167], v[240:243], v[106:109]
	v_mfma_f32_16x16x32_bf16 v[102:105], v[156:159], v[194:197], v[102:105]
	v_mfma_f32_16x16x32_bf16 v[98:101], v[164:167], v[194:197], v[98:101]
	v_mfma_f32_16x16x32_bf16 v[94:97], v[168:171], v[206:209], v[94:97]
	v_mfma_f32_16x16x32_bf16 v[90:93], v[176:179], v[206:209], v[90:93]
	v_mfma_f32_16x16x32_bf16 v[86:89], v[168:171], v[214:217], v[86:89]
	v_mfma_f32_16x16x32_bf16 v[82:85], v[176:179], v[214:217], v[82:85]
	v_mfma_f32_16x16x32_bf16 v[78:81], v[168:171], v[236:239], v[78:81]
	v_mfma_f32_16x16x32_bf16 v[74:77], v[176:179], v[236:239], v[74:77]
	v_mfma_f32_16x16x32_bf16 v[70:73], v[168:171], v[244:247], v[70:73]
	v_mfma_f32_16x16x32_bf16 v[66:69], v[176:179], v[244:247], v[66:69]
	v_mfma_f32_16x16x32_bf16 v[94:97], v[172:175], v[210:213], v[94:97]
	v_mfma_f32_16x16x32_bf16 v[90:93], v[180:183], v[210:213], v[90:93]
	v_mfma_f32_16x16x32_bf16 v[86:89], v[172:175], v[218:221], v[86:89]
	v_mfma_f32_16x16x32_bf16 v[82:85], v[180:183], v[218:221], v[82:85]
	v_mfma_f32_16x16x32_bf16 v[78:81], v[172:175], v[240:243], v[78:81]
	v_mfma_f32_16x16x32_bf16 v[74:77], v[180:183], v[240:243], v[74:77]
	v_mfma_f32_16x16x32_bf16 v[70:73], v[172:175], v[194:197], v[70:73]
	v_mfma_f32_16x16x32_bf16 v[66:69], v[180:183], v[194:197], v[66:69]
	s_setprio 1
	s_barrier
	s_add_i32 s10, s13, s42
	v_lshl_add_u64 v[184:185], s[84:85], 0, v[130:131]
	s_mov_b32 m0, s10
	ds_read_b128 v[194:197], v151 offset:16384
	ds_read_b128 v[206:209], v151 offset:17408
	ds_read_b128 v[210:213], v151 offset:18432
	ds_read_b128 v[214:217], v151 offset:19456
	ds_read_b128 v[218:221], v151 offset:20480
	ds_read_b128 v[236:239], v151 offset:21504
	ds_read_b128 v[240:243], v151 offset:22528
	ds_read_b128 v[244:247], v151 offset:23552
	global_load_lds_dwordx4 v[184:185], off
	s_add_i32 m0, s10, 0x2000
	s_add_u32 s10, s84, 0x20000
	v_lshl_add_u64 v[198:199], s[84:85], 0, v[134:135]
	s_addc_u32 s11, s85, 0
	s_add_i32 s9, s9, s42
	global_load_lds_dwordx4 v[198:199], off
	v_lshl_add_u64 v[222:223], s[10:11], 0, v[130:131]
	s_mov_b32 m0, s9
	v_lshl_add_u64 v[234:235], s[92:93], 0, v[132:133]
	global_load_lds_dwordx4 v[222:223], off
	v_lshl_add_u64 v[222:223], s[10:11], 0, v[134:135]
	s_add_i32 m0, s9, 0x2000
	s_nop 0
	global_load_lds_dwordx4 v[222:223], off
	v_lshl_add_u64 v[222:223], s[92:93], 0, v[190:191]
	s_mov_b32 m0, s51
	s_nop 0
	global_load_lds_dwordx4 v[222:223], off
	s_mov_b32 m0, s67
	s_nop 0
	global_load_lds_dwordx4 v[234:235], off
	s_waitcnt vmcnt(8)
	s_waitcnt lgkmcnt(0)
	s_barrier
; #define PG8_STAGE(bufoff, gbase, voff) do { _Pragma("unroll") for (int _i = 0; _i < 2; ++_i) \
;         __builtin_amdgcn_global_load_lds((const unsigned*)((const char*)(gbase) + (voff)[_i]), (PG8_LAS unsigned*)(lds + (bufoff) + ldsw + _i * 8192), 16, 0, 0); } while (0)
; #define PG8_LDA(dst, b, h) do { _Pragma("unroll") for (int m = 0; m < 4; ++m) _Pragma("unroll") for (int k = 0; k < 2; ++k) dst[m][k] = *(const PG8_LAS bf16x8*)(lds + PG8_SA(b, h) + aoff + m * 2048 + k * 1024); } while (0)
; #define PG8_LDB(dst, b, h) do { _Pragma("unroll") for (int n = 0; n < 2; ++n) _Pragma("unroll") for (int k = 0; k < 2; ++k) dst[n][k] = *(const PG8_LAS bf16x8*)(lds + PG8_SB(b, h) + boff + n * 2048 + k * 1024); } while (0)
; #define PG8_MMA(ai, bj, At, Bt) do { __builtin_amdgcn_s_setprio(1); _Pragma("unroll") for (int m = 0; m < 4; ++m) _Pragma("unroll") for (int n = 0; n < 2; ++n) _Pragma("unroll") for (int k = 0; k < 2; ++k) \
;         acc[ai][bj][m][n] = __builtin_amdgcn_mfma_f32_16x16x32_bf16(Bt[n][k], At[m][k], acc[ai][bj][m][n], 0, 0, 0); __builtin_amdgcn_s_setprio(0); } while (0)
; #define PG8_WAIT_V(n) asm volatile("s_waitcnt vmcnt(" #n ")" ::: "memory")
; #define PG8_WAIT_L(n) asm volatile("s_waitcnt lgkmcnt(" #n ")" ::: "memory")
; #define PG8_BAR __builtin_amdgcn_s_barrier()
; #define PG8_SCHED __builtin_amdgcn_sched_barrier(0)
; template <class Epi, class Sched, bool ALIGN_EPI = false, bool SP2 = false>
; __device__ __forceinline__ void gemm_phase(PG8_LAS unsigned char* lds, const Gemm g, const Sched& S, const Epi& E) {
;     ...
;             PG8_WAIT_V(8); PG8_WAIT_L(0); PG8_BAR; PG8_MMA(1, 0, At, B0); PG8_MMA(1, 1, At, B1); PG8_BAR; PG8_SCHED;
;             PG8_LDB(B0, 1, 0); PG8_LDB(B1, 1, 1); PG8_SCHED; PG8_LDA(At, 1, 0); PG8_STAGE(PG8_SA(0, 1), a2 + hstep, voffA);
;             PG8_WAIT_V(8); PG8_WAIT_L(0); PG8_BAR; PG8_MMA(0, 0, At, B0); PG8_MMA(0, 1, At, B1); PG8_BAR; PG8_SCHED;
	s_setprio 0
	s_waitcnt lgkmcnt(0)
	v_mfma_f32_16x16x32_bf16 v[62:65], v[152:155], v[194:197], v[62:65]
	v_mfma_f32_16x16x32_bf16 v[58:61], v[160:163], v[194:197], v[58:61]
	v_mfma_f32_16x16x32_bf16 v[54:57], v[152:155], v[210:213], v[54:57]
	v_mfma_f32_16x16x32_bf16 v[50:53], v[160:163], v[210:213], v[50:53]
	v_mfma_f32_16x16x32_bf16 v[46:49], v[152:155], v[218:221], v[46:49]
	v_mfma_f32_16x16x32_bf16 v[42:45], v[160:163], v[218:221], v[42:45]
	v_mfma_f32_16x16x32_bf16 v[38:41], v[152:155], v[240:243], v[38:41]
	v_mfma_f32_16x16x32_bf16 v[34:37], v[160:163], v[240:243], v[34:37]
	v_mfma_f32_16x16x32_bf16 v[62:65], v[156:159], v[206:209], v[62:65]
	v_mfma_f32_16x16x32_bf16 v[58:61], v[164:167], v[206:209], v[58:61]
	v_mfma_f32_16x16x32_bf16 v[54:57], v[156:159], v[214:217], v[54:57]
	v_mfma_f32_16x16x32_bf16 v[50:53], v[164:167], v[214:217], v[50:53]
	v_mfma_f32_16x16x32_bf16 v[46:49], v[156:159], v[236:239], v[46:49]
	v_mfma_f32_16x16x32_bf16 v[42:45], v[164:167], v[236:239], v[42:45]
	v_mfma_f32_16x16x32_bf16 v[38:41], v[156:159], v[244:247], v[38:41]
	v_mfma_f32_16x16x32_bf16 v[34:37], v[164:167], v[244:247], v[34:37]
	v_mfma_f32_16x16x32_bf16 v[30:33], v[168:171], v[194:197], v[30:33]
	v_mfma_f32_16x16x32_bf16 v[26:29], v[176:179], v[194:197], v[26:29]
	v_mfma_f32_16x16x32_bf16 v[22:25], v[168:171], v[210:213], v[22:25]
	v_mfma_f32_16x16x32_bf16 v[18:21], v[176:179], v[210:213], v[18:21]
	v_mfma_f32_16x16x32_bf16 v[14:17], v[168:171], v[218:221], v[14:17]
	v_mfma_f32_16x16x32_bf16 v[10:13], v[176:179], v[218:221], v[10:13]
	v_mfma_f32_16x16x32_bf16 v[6:9], v[168:171], v[240:243], v[6:9]
	v_mfma_f32_16x16x32_bf16 v[2:5], v[176:179], v[240:243], v[2:5]
	v_mfma_f32_16x16x32_bf16 v[30:33], v[172:175], v[206:209], v[30:33]
	v_mfma_f32_16x16x32_bf16 v[26:29], v[180:183], v[206:209], v[26:29]
	v_mfma_f32_16x16x32_bf16 v[22:25], v[172:175], v[214:217], v[22:25]
	v_mfma_f32_16x16x32_bf16 v[18:21], v[180:183], v[214:217], v[18:21]
	v_mfma_f32_16x16x32_bf16 v[14:17], v[172:175], v[236:239], v[14:17]
	v_mfma_f32_16x16x32_bf16 v[10:13], v[180:183], v[236:239], v[10:13]
	v_mfma_f32_16x16x32_bf16 v[6:9], v[172:175], v[244:247], v[6:9]
	v_mfma_f32_16x16x32_bf16 v[2:5], v[180:183], v[244:247], v[2:5]
	s_setprio 1
	s_barrier
	s_add_i32 s9, 0, 0x18000
	v_add_u32_e32 v144, s9, v145
	s_add_i32 s12, 0, 0x1c000
	ds_read_b128 v[152:155], v144
	ds_read_b128 v[156:159], v144 offset:1024
	ds_read_b128 v[160:163], v144 offset:2048
	ds_read_b128 v[164:167], v144 offset:3072
	v_add_u32_e32 v144, s12, v145
	ds_read_b128 v[168:171], v144
	ds_read_b128 v[172:175], v144 offset:1024
	ds_read_b128 v[176:179], v144 offset:2048
	ds_read_b128 v[180:183], v144 offset:3072
	s_add_u32 s10, s92, 0x80000
	s_addc_u32 s11, s93, 0
	s_mov_b32 m0, s74
	v_lshl_add_u64 v[186:187], s[10:11], 0, v[190:191]
	ds_read_b128 v[194:197], v151 offset:32768
	ds_read_b128 v[206:209], v151 offset:33792
	ds_read_b128 v[210:213], v151 offset:34816
	ds_read_b128 v[214:217], v151 offset:35840
	ds_read_b128 v[218:221], v151 offset:36864
	ds_read_b128 v[236:239], v151 offset:37888
	ds_read_b128 v[240:243], v151 offset:38912
	ds_read_b128 v[244:247], v151 offset:39936
	global_load_lds_dwordx4 v[186:187], off
	v_lshl_add_u64 v[186:187], s[10:11], 0, v[132:133]
	s_mov_b32 m0, s75
	s_nop 0
	global_load_lds_dwordx4 v[186:187], off
	s_waitcnt vmcnt(8)
	s_waitcnt lgkmcnt(0)
	s_barrier
	s_setprio 0
	s_waitcnt lgkmcnt(0)
	v_mfma_f32_16x16x32_bf16 v[126:129], v[152:155], v[194:197], v[126:129]
	v_mfma_f32_16x16x32_bf16 v[122:125], v[160:163], v[194:197], v[122:125]
	v_mfma_f32_16x16x32_bf16 v[118:121], v[152:155], v[210:213], v[118:121]
	v_mfma_f32_16x16x32_bf16 v[114:117], v[160:163], v[210:213], v[114:117]
	v_mfma_f32_16x16x32_bf16 v[110:113], v[152:155], v[218:221], v[110:113]
	v_mfma_f32_16x16x32_bf16 v[106:109], v[160:163], v[218:221], v[106:109]
	v_mfma_f32_16x16x32_bf16 v[102:105], v[152:155], v[240:243], v[102:105]
	v_mfma_f32_16x16x32_bf16 v[98:101], v[160:163], v[240:243], v[98:101]
	v_mfma_f32_16x16x32_bf16 v[126:129], v[156:159], v[206:209], v[126:129]
	v_mfma_f32_16x16x32_bf16 v[122:125], v[164:167], v[206:209], v[122:125]
	v_mfma_f32_16x16x32_bf16 v[118:121], v[156:159], v[214:217], v[118:121]
	v_mfma_f32_16x16x32_bf16 v[114:117], v[164:167], v[214:217], v[114:117]
	v_mfma_f32_16x16x32_bf16 v[110:113], v[156:159], v[236:239], v[110:113]
	v_mfma_f32_16x16x32_bf16 v[106:109], v[164:167], v[236:239], v[106:109]
	v_mfma_f32_16x16x32_bf16 v[102:105], v[156:159], v[244:247], v[102:105]
	v_mfma_f32_16x16x32_bf16 v[98:101], v[164:167], v[244:247], v[98:101]
	v_mfma_f32_16x16x32_bf16 v[94:97], v[168:171], v[194:197], v[94:97]
	v_mfma_f32_16x16x32_bf16 v[90:93], v[176:179], v[194:197], v[90:93]
	v_mfma_f32_16x16x32_bf16 v[86:89], v[168:171], v[210:213], v[86:89]
	v_mfma_f32_16x16x32_bf16 v[82:85], v[176:179], v[210:213], v[82:85]
	v_mfma_f32_16x16x32_bf16 v[78:81], v[168:171], v[218:221], v[78:81]
	v_mfma_f32_16x16x32_bf16 v[74:77], v[176:179], v[218:221], v[74:77]
	v_mfma_f32_16x16x32_bf16 v[70:73], v[168:171], v[240:243], v[70:73]
	v_mfma_f32_16x16x32_bf16 v[66:69], v[176:179], v[240:243], v[66:69]
	v_mfma_f32_16x16x32_bf16 v[94:97], v[172:175], v[206:209], v[94:97]
	v_mfma_f32_16x16x32_bf16 v[90:93], v[180:183], v[206:209], v[90:93]
	v_mfma_f32_16x16x32_bf16 v[86:89], v[172:175], v[214:217], v[86:89]
	v_mfma_f32_16x16x32_bf16 v[82:85], v[180:183], v[214:217], v[82:85]
	v_mfma_f32_16x16x32_bf16 v[78:81], v[172:175], v[236:239], v[78:81]
	v_mfma_f32_16x16x32_bf16 v[74:77], v[180:183], v[236:239], v[74:77]
	v_mfma_f32_16x16x32_bf16 v[70:73], v[172:175], v[244:247], v[70:73]
	v_mfma_f32_16x16x32_bf16 v[66:69], v[180:183], v[244:247], v[66:69]
	s_setprio 1
	s_barrier
; #define PG8_STAGE(bufoff, gbase, voff) do { _Pragma("unroll") for (int _i = 0; _i < 2; ++_i) \
;         __builtin_amdgcn_global_load_lds((const unsigned*)((const char*)(gbase) + (voff)[_i]), (PG8_LAS unsigned*)(lds + (bufoff) + ldsw + _i * 8192), 16, 0, 0); } while (0)
; #define PG8_LDA(dst, b, h) do { _Pragma("unroll") for (int m = 0; m < 4; ++m) _Pragma("unroll") for (int k = 0; k < 2; ++k) dst[m][k] = *(const PG8_LAS bf16x8*)(lds + PG8_SA(b, h) + aoff + m * 2048 + k * 1024); } while (0)
; #define PG8_MMA(ai, bj, At, Bt) do { __builtin_amdgcn_s_setprio(1); _Pragma("unroll") for (int m = 0; m < 4; ++m) _Pragma("unroll") for (int n = 0; n < 2; ++n) _Pragma("unroll") for (int k = 0; k < 2; ++k) \
;         acc[ai][bj][m][n] = __builtin_amdgcn_mfma_f32_16x16x32_bf16(Bt[n][k], At[m][k], acc[ai][bj][m][n], 0, 0, 0); __builtin_amdgcn_s_setprio(0); } while (0)
; #define PG8_WAIT_V(n) asm volatile("s_waitcnt vmcnt(" #n ")" ::: "memory")
; #define PG8_WAIT_L(n) asm volatile("s_waitcnt lgkmcnt(" #n ")" ::: "memory")
; #define PG8_BAR __builtin_amdgcn_s_barrier()
; #define PG8_SCHED __builtin_amdgcn_sched_barrier(0)
; template <class Epi, class Sched, bool ALIGN_EPI = false, bool SP2 = false>
; __device__ __forceinline__ void gemm_phase(PG8_LAS unsigned char* lds, const Gemm g, const Sched& S, const Epi& E) {
;     ...
;             PG8_LDA(At, 1, 1); PG8_STAGE(PG8_SB(1, 0), b3, voffB); PG8_STAGE(PG8_SB(1, 1), b3 + hstepB, voffB); PG8_STAGE(PG8_SA(1, 0), a3, voffA);
;             PG8_WAIT_V(8); PG8_WAIT_L(0); PG8_BAR; PG8_MMA(1, 0, At, B0); PG8_MMA(1, 1, At, B1); PG8_BAR; PG8_SCHED;
	s_add_i32 s9, s9, s42
	v_lshl_add_u64 v[184:185], v[184:185], 0, s[60:61]
	s_mov_b32 m0, s9
	ds_read_b128 v[194:197], v151 offset:49152
	ds_read_b128 v[206:209], v151 offset:50176
	ds_read_b128 v[210:213], v151 offset:51200
	ds_read_b128 v[214:217], v151 offset:52224
	ds_read_b128 v[218:221], v151 offset:53248
	ds_read_b128 v[236:239], v151 offset:54272
	ds_read_b128 v[240:243], v151 offset:55296
	ds_read_b128 v[244:247], v151 offset:56320
	global_load_lds_dwordx4 v[184:185], off
	s_add_i32 m0, s9, 0x2000
	s_add_u32 s10, s84, 0x20080
	v_lshl_add_u64 v[184:185], v[198:199], 0, s[60:61]
	s_addc_u32 s11, s85, 0
	s_add_i32 s9, s12, s42
	global_load_lds_dwordx4 v[184:185], off
	v_lshl_add_u64 v[184:185], s[10:11], 0, v[130:131]
	s_mov_b32 m0, s9
	s_nop 0
	global_load_lds_dwordx4 v[184:185], off
	v_lshl_add_u64 v[184:185], s[10:11], 0, v[134:135]
	s_add_i32 m0, s9, 0x2000
	s_nop 0
	global_load_lds_dwordx4 v[184:185], off
	v_lshl_add_u64 v[184:185], v[222:223], 0, s[60:61]
	s_mov_b32 m0, s82
	s_nop 0
	global_load_lds_dwordx4 v[184:185], off
	v_lshl_add_u64 v[184:185], v[234:235], 0, s[60:61]
	s_mov_b32 m0, s86
	s_nop 0
	global_load_lds_dwordx4 v[184:185], off
	s_waitcnt vmcnt(8)
	s_waitcnt lgkmcnt(0)
	s_barrier
	s_setprio 0
	s_waitcnt lgkmcnt(0)
	v_mfma_f32_16x16x32_bf16 v[62:65], v[152:155], v[194:197], v[62:65]
	v_mfma_f32_16x16x32_bf16 v[58:61], v[160:163], v[194:197], v[58:61]
	v_mfma_f32_16x16x32_bf16 v[54:57], v[152:155], v[210:213], v[54:57]
	v_mfma_f32_16x16x32_bf16 v[50:53], v[160:163], v[210:213], v[50:53]
	v_mfma_f32_16x16x32_bf16 v[46:49], v[152:155], v[218:221], v[46:49]
	v_mfma_f32_16x16x32_bf16 v[42:45], v[160:163], v[218:221], v[42:45]
	v_mfma_f32_16x16x32_bf16 v[38:41], v[152:155], v[240:243], v[38:41]
	v_mfma_f32_16x16x32_bf16 v[34:37], v[160:163], v[240:243], v[34:37]
	v_mfma_f32_16x16x32_bf16 v[62:65], v[156:159], v[206:209], v[62:65]
	v_mfma_f32_16x16x32_bf16 v[58:61], v[164:167], v[206:209], v[58:61]
	v_mfma_f32_16x16x32_bf16 v[54:57], v[156:159], v[214:217], v[54:57]
	v_mfma_f32_16x16x32_bf16 v[50:53], v[164:167], v[214:217], v[50:53]
	v_mfma_f32_16x16x32_bf16 v[46:49], v[156:159], v[236:239], v[46:49]
	v_mfma_f32_16x16x32_bf16 v[42:45], v[164:167], v[236:239], v[42:45]
	v_mfma_f32_16x16x32_bf16 v[38:41], v[156:159], v[244:247], v[38:41]
	v_mfma_f32_16x16x32_bf16 v[34:37], v[164:167], v[244:247], v[34:37]
	v_mfma_f32_16x16x32_bf16 v[30:33], v[168:171], v[194:197], v[30:33]
	v_mfma_f32_16x16x32_bf16 v[26:29], v[176:179], v[194:197], v[26:29]
	v_mfma_f32_16x16x32_bf16 v[22:25], v[168:171], v[210:213], v[22:25]
	v_mfma_f32_16x16x32_bf16 v[18:21], v[176:179], v[210:213], v[18:21]
	v_mfma_f32_16x16x32_bf16 v[14:17], v[168:171], v[218:221], v[14:17]
	v_mfma_f32_16x16x32_bf16 v[10:13], v[176:179], v[218:221], v[10:13]
	v_mfma_f32_16x16x32_bf16 v[6:9], v[168:171], v[240:243], v[6:9]
	v_mfma_f32_16x16x32_bf16 v[2:5], v[176:179], v[240:243], v[2:5]
	v_mfma_f32_16x16x32_bf16 v[30:33], v[172:175], v[206:209], v[30:33]
	v_mfma_f32_16x16x32_bf16 v[26:29], v[180:183], v[206:209], v[26:29]
	v_mfma_f32_16x16x32_bf16 v[22:25], v[172:175], v[214:217], v[22:25]
	v_mfma_f32_16x16x32_bf16 v[18:21], v[180:183], v[214:217], v[18:21]
	v_mfma_f32_16x16x32_bf16 v[14:17], v[172:175], v[236:239], v[14:17]
	v_mfma_f32_16x16x32_bf16 v[10:13], v[180:183], v[236:239], v[10:13]
	v_mfma_f32_16x16x32_bf16 v[6:9], v[172:175], v[244:247], v[6:9]
	v_mfma_f32_16x16x32_bf16 v[2:5], v[180:183], v[244:247], v[2:5]
	s_setprio 1
	s_barrier
	s_add_i32 s8, s8, 2
	s_add_u32 s80, s80, 0x100
	s_addc_u32 s81, s81, 0
	s_cmp_gt_u32 s8, 29
	s_cbranch_scc0 .LBB0_1233
	s_setprio 0
	s_and_b64 vcc, exec, s[62:63]
	s_cbranch_vccz .LBB0_1236
	s_barrier
